# speedup vs baseline: 1.0385x; 1.0051x over previous
.Lglds_2829:
	s_add_i32 s0, s5, 0x40
	s_lshl_b32 s0, s0, 1
	s_setprio 1
	ds_read_b128 v[154:157], v112 offset:16384
	ds_read_b128 v[158:161], v112 offset:18432
	ds_read_b128 v[162:165], v110
	ds_read_b128 v[166:169], v110 offset:2048
	ds_read_b128 v[170:173], v112 offset:20480
	ds_read_b128 v[174:177], v113 offset:16384
	s_waitcnt lgkmcnt(3)
	v_mfma_f32_16x16x32_bf16 v[94:97], v[154:157], v[162:165], v[94:97]
	s_add_u32 m0, s6, 0x8000
	v_lshl_add_u64 v[204:205], v[188:189], 0, s[0:1]
	global_load_lds_dwordx4 v[204:205], off
	v_mfma_f32_16x16x32_bf16 v[90:93], v[158:161], v[162:165], v[90:93]
	s_waitcnt lgkmcnt(1)
	v_mfma_f32_16x16x32_bf16 v[86:89], v[170:173], v[162:165], v[86:89]
	s_waitcnt lgkmcnt(0)
	v_mfma_f32_16x16x32_bf16 v[82:85], v[174:177], v[162:165], v[82:85]
	s_add_u32 m0, s6, 0x9000
	v_lshl_add_u64 v[206:207], v[190:191], 0, s[0:1]
	global_load_lds_dwordx4 v[206:207], off
	v_mfma_f32_16x16x32_bf16 v[78:81], v[154:157], v[166:169], v[78:81]
	v_mfma_f32_16x16x32_bf16 v[62:65], v[158:161], v[166:169], v[62:65]
	v_mfma_f32_16x16x32_bf16 v[46:49], v[170:173], v[166:169], v[46:49]
	s_add_u32 m0, s6, 0xa000
	v_lshl_add_u64 v[204:205], v[192:193], 0, s[0:1]
	global_load_lds_dwordx4 v[204:205], off
	v_mfma_f32_16x16x32_bf16 v[26:29], v[174:177], v[166:169], v[26:29]
	ds_read_b128 v[162:165], v110 offset:4096
	ds_read_b128 v[166:169], v111
	s_waitcnt lgkmcnt(1)
	v_mfma_f32_16x16x32_bf16 v[38:41], v[154:157], v[162:165], v[38:41]
	v_mfma_f32_16x16x32_bf16 v[30:33], v[158:161], v[162:165], v[30:33]
	s_add_u32 m0, s6, 0xb000
	v_lshl_add_u64 v[206:207], v[194:195], 0, s[0:1]
	global_load_lds_dwordx4 v[206:207], off
	v_mfma_f32_16x16x32_bf16 v[22:25], v[170:173], v[162:165], v[22:25]
	v_mfma_f32_16x16x32_bf16 v[18:21], v[174:177], v[162:165], v[18:21]
	s_waitcnt lgkmcnt(0)
	v_mfma_f32_16x16x32_bf16 v[14:17], v[154:157], v[166:169], v[14:17]
	s_add_u32 m0, s6, 0xc000
	v_lshl_add_u64 v[204:205], v[196:197], 0, s[0:1]
	global_load_lds_dwordx4 v[204:205], off
	ds_read_b128 v[154:157], v116 offset:16384
	v_mfma_f32_16x16x32_bf16 v[10:13], v[158:161], v[166:169], v[10:13]
	v_mfma_f32_16x16x32_bf16 v[6:9], v[170:173], v[166:169], v[6:9]
	v_mfma_f32_16x16x32_bf16 v[2:5], v[174:177], v[166:169], v[2:5]
	s_add_u32 m0, s6, 0xd000
	v_lshl_add_u64 v[206:207], v[198:199], 0, s[0:1]
	global_load_lds_dwordx4 v[206:207], off
	ds_read_b128 v[158:161], v116 offset:18432
	ds_read_b128 v[162:165], v114
	ds_read_b128 v[166:169], v114 offset:2048
	ds_read_b128 v[170:173], v116 offset:20480
	ds_read_b128 v[174:177], v117 offset:16384
	s_waitcnt lgkmcnt(3)
	v_mfma_f32_16x16x32_bf16 v[94:97], v[154:157], v[162:165], v[94:97]
	v_mfma_f32_16x16x32_bf16 v[90:93], v[158:161], v[162:165], v[90:93]
	s_waitcnt lgkmcnt(1)
	v_mfma_f32_16x16x32_bf16 v[86:89], v[170:173], v[162:165], v[86:89]
	s_add_u32 m0, s6, 0xe000
	v_lshl_add_u64 v[204:205], v[200:201], 0, s[0:1]
	global_load_lds_dwordx4 v[204:205], off
	s_waitcnt lgkmcnt(0)
	v_mfma_f32_16x16x32_bf16 v[82:85], v[174:177], v[162:165], v[82:85]
	v_mfma_f32_16x16x32_bf16 v[78:81], v[154:157], v[166:169], v[78:81]
	v_mfma_f32_16x16x32_bf16 v[62:65], v[158:161], v[166:169], v[62:65]
	s_add_u32 m0, s6, 0xf000
	v_lshl_add_u64 v[206:207], v[202:203], 0, s[0:1]
	global_load_lds_dwordx4 v[206:207], off
	v_mfma_f32_16x16x32_bf16 v[46:49], v[170:173], v[166:169], v[46:49]
	v_mfma_f32_16x16x32_bf16 v[26:29], v[174:177], v[166:169], v[26:29]
	ds_read_b128 v[162:165], v114 offset:4096
	ds_read_b128 v[166:169], v115
	s_waitcnt lgkmcnt(1)
	v_mfma_f32_16x16x32_bf16 v[38:41], v[154:157], v[162:165], v[38:41]
	v_mfma_f32_16x16x32_bf16 v[30:33], v[158:161], v[162:165], v[30:33]
	v_mfma_f32_16x16x32_bf16 v[22:25], v[170:173], v[162:165], v[22:25]
	v_mfma_f32_16x16x32_bf16 v[18:21], v[174:177], v[162:165], v[18:21]
	s_waitcnt lgkmcnt(0)
	v_mfma_f32_16x16x32_bf16 v[14:17], v[154:157], v[166:169], v[14:17]
	v_mfma_f32_16x16x32_bf16 v[10:13], v[158:161], v[166:169], v[10:13]
	v_mfma_f32_16x16x32_bf16 v[6:9], v[170:173], v[166:169], v[6:9]
	v_mfma_f32_16x16x32_bf16 v[2:5], v[174:177], v[166:169], v[2:5]
	s_setprio 0
	s_waitcnt vmcnt(0)
	s_barrier
	s_add_i32 s0, s5, 0x80
	s_min_u32 s0, s0, 0x3c0
	s_lshl_b32 s0, s0, 1
	s_setprio 1
	ds_read_b128 v[154:157], v112 offset:49152
	ds_read_b128 v[158:161], v112 offset:51200
	ds_read_b128 v[162:165], v110 offset:32768
	ds_read_b128 v[166:169], v110 offset:34816
	ds_read_b128 v[170:173], v112 offset:53248
	ds_read_b128 v[174:177], v113 offset:49152
	s_waitcnt lgkmcnt(3)
	v_mfma_f32_16x16x32_bf16 v[94:97], v[154:157], v[162:165], v[94:97]
	s_add_u32 m0, s6, 0x0
	v_lshl_add_u64 v[204:205], v[188:189], 0, s[0:1]
	global_load_lds_dwordx4 v[204:205], off
	v_mfma_f32_16x16x32_bf16 v[90:93], v[158:161], v[162:165], v[90:93]
	s_waitcnt lgkmcnt(1)
	v_mfma_f32_16x16x32_bf16 v[86:89], v[170:173], v[162:165], v[86:89]
	s_waitcnt lgkmcnt(0)
	v_mfma_f32_16x16x32_bf16 v[82:85], v[174:177], v[162:165], v[82:85]
	s_add_u32 m0, s6, 0x1000
	v_lshl_add_u64 v[206:207], v[190:191], 0, s[0:1]
	global_load_lds_dwordx4 v[206:207], off
	v_mfma_f32_16x16x32_bf16 v[78:81], v[154:157], v[166:169], v[78:81]
	v_mfma_f32_16x16x32_bf16 v[62:65], v[158:161], v[166:169], v[62:65]
	v_mfma_f32_16x16x32_bf16 v[46:49], v[170:173], v[166:169], v[46:49]
	s_add_u32 m0, s6, 0x2000
	v_lshl_add_u64 v[204:205], v[192:193], 0, s[0:1]
	global_load_lds_dwordx4 v[204:205], off
	v_mfma_f32_16x16x32_bf16 v[26:29], v[174:177], v[166:169], v[26:29]
	ds_read_b128 v[162:165], v110 offset:36864
	ds_read_b128 v[166:169], v111 offset:32768
	s_waitcnt lgkmcnt(1)
	v_mfma_f32_16x16x32_bf16 v[38:41], v[154:157], v[162:165], v[38:41]
	v_mfma_f32_16x16x32_bf16 v[30:33], v[158:161], v[162:165], v[30:33]
	s_add_u32 m0, s6, 0x3000
	v_lshl_add_u64 v[206:207], v[194:195], 0, s[0:1]
	global_load_lds_dwordx4 v[206:207], off
	v_mfma_f32_16x16x32_bf16 v[22:25], v[170:173], v[162:165], v[22:25]
	v_mfma_f32_16x16x32_bf16 v[18:21], v[174:177], v[162:165], v[18:21]
	s_waitcnt lgkmcnt(0)
	v_mfma_f32_16x16x32_bf16 v[14:17], v[154:157], v[166:169], v[14:17]
	s_add_u32 m0, s6, 0x4000
	v_lshl_add_u64 v[204:205], v[196:197], 0, s[0:1]
	global_load_lds_dwordx4 v[204:205], off
	ds_read_b128 v[154:157], v116 offset:49152
	v_mfma_f32_16x16x32_bf16 v[10:13], v[158:161], v[166:169], v[10:13]
	v_mfma_f32_16x16x32_bf16 v[6:9], v[170:173], v[166:169], v[6:9]
	v_mfma_f32_16x16x32_bf16 v[2:5], v[174:177], v[166:169], v[2:5]
	s_add_u32 m0, s6, 0x5000
	v_lshl_add_u64 v[206:207], v[198:199], 0, s[0:1]
	global_load_lds_dwordx4 v[206:207], off
	ds_read_b128 v[158:161], v116 offset:51200
	ds_read_b128 v[162:165], v114 offset:32768
	ds_read_b128 v[166:169], v114 offset:34816
	ds_read_b128 v[170:173], v116 offset:53248
	ds_read_b128 v[174:177], v117 offset:49152
	s_waitcnt lgkmcnt(3)
	v_mfma_f32_16x16x32_bf16 v[94:97], v[154:157], v[162:165], v[94:97]
	v_mfma_f32_16x16x32_bf16 v[90:93], v[158:161], v[162:165], v[90:93]
	s_waitcnt lgkmcnt(1)
	v_mfma_f32_16x16x32_bf16 v[86:89], v[170:173], v[162:165], v[86:89]
	s_add_u32 m0, s6, 0x6000
	v_lshl_add_u64 v[204:205], v[200:201], 0, s[0:1]
	global_load_lds_dwordx4 v[204:205], off
	s_waitcnt lgkmcnt(0)
	v_mfma_f32_16x16x32_bf16 v[82:85], v[174:177], v[162:165], v[82:85]
	v_mfma_f32_16x16x32_bf16 v[78:81], v[154:157], v[166:169], v[78:81]
	v_mfma_f32_16x16x32_bf16 v[62:65], v[158:161], v[166:169], v[62:65]
	s_add_u32 m0, s6, 0x7000
	v_lshl_add_u64 v[206:207], v[202:203], 0, s[0:1]
	global_load_lds_dwordx4 v[206:207], off
	v_mfma_f32_16x16x32_bf16 v[46:49], v[170:173], v[166:169], v[46:49]
	v_mfma_f32_16x16x32_bf16 v[26:29], v[174:177], v[166:169], v[26:29]
	ds_read_b128 v[162:165], v114 offset:36864
	ds_read_b128 v[166:169], v115 offset:32768
	s_waitcnt lgkmcnt(1)
	v_mfma_f32_16x16x32_bf16 v[38:41], v[154:157], v[162:165], v[38:41]
	v_mfma_f32_16x16x32_bf16 v[30:33], v[158:161], v[162:165], v[30:33]
	v_mfma_f32_16x16x32_bf16 v[22:25], v[170:173], v[162:165], v[22:25]
	v_mfma_f32_16x16x32_bf16 v[18:21], v[174:177], v[162:165], v[18:21]
	s_waitcnt lgkmcnt(0)
	v_mfma_f32_16x16x32_bf16 v[14:17], v[154:157], v[166:169], v[14:17]
	v_mfma_f32_16x16x32_bf16 v[10:13], v[158:161], v[166:169], v[10:13]
	v_mfma_f32_16x16x32_bf16 v[6:9], v[170:173], v[166:169], v[6:9]
	v_mfma_f32_16x16x32_bf16 v[2:5], v[174:177], v[166:169], v[2:5]
	s_setprio 0
	s_add_i32 s5, s5, 0x80
	s_add_i32 s4, s4, 2
	s_waitcnt vmcnt(0)
	s_barrier
	s_cmp_gt_u32 s4, 13
	s_cbranch_scc0 .Lglds_2829
	v_readlane_b32 s36, v254, 40
	s_waitcnt vmcnt(7)
	v_or_b32_e32 v35, s2, v118
	v_readlane_b32 s48, v254, 52
	v_readlane_b32 s49, v254, 53
	v_or_b32_e32 v34, s3, v119
	s_waitcnt vmcnt(6)
	v_add_u32_e32 v42, v35, v120
	v_mov_b64_e32 v[36:37], s[48:49]
	v_mad_i64_i32 v[36:37], s[2:3], v42, s18, v[36:37]
	v_cmp_gt_i32_e32 vcc, s19, v34
	v_ashrrev_i32_e32 v35, 31, v34
	v_readlane_b32 s37, v254, 41
	v_readlane_b32 s38, v254, 42
	v_readlane_b32 s39, v254, 43
	v_readlane_b32 s40, v254, 44
	v_readlane_b32 s41, v254, 45
	v_readlane_b32 s42, v254, 46
	v_readlane_b32 s43, v254, 47
	v_readlane_b32 s44, v254, 48
	v_readlane_b32 s45, v254, 49
	v_readlane_b32 s46, v254, 50
	v_readlane_b32 s47, v254, 51
	v_readlane_b32 s50, v254, 54
	v_readlane_b32 s51, v254, 55
	s_and_saveexec_b64 s[2:3], vcc
	s_cbranch_execnz .LBB0_205
	s_or_b64 exec, exec, s[2:3]
	v_cmp_gt_i32_e64 s[4:5], s20, v34
	s_and_saveexec_b64 s[2:3], s[4:5]
	s_cbranch_execnz .LBB0_206

.Lglds_3547:
	s_add_i32 s0, s19, 0x40
	s_lshl_b32 s0, s0, 1
	s_setprio 1
	ds_read_b128 v[152:155], v112 offset:16384
	ds_read_b128 v[156:159], v112 offset:18432
	ds_read_b128 v[160:163], v110
	ds_read_b128 v[164:167], v110 offset:2048
	ds_read_b128 v[168:171], v112 offset:20480
	ds_read_b128 v[172:175], v113 offset:16384
	s_waitcnt lgkmcnt(3)
	v_mfma_f32_16x16x32_bf16 v[94:97], v[152:155], v[160:163], v[94:97]
	s_add_u32 m0, s20, 0x8000
	v_lshl_add_u64 v[204:205], v[188:189], 0, s[0:1]
	global_load_lds_dwordx4 v[204:205], off
	v_mfma_f32_16x16x32_bf16 v[90:93], v[156:159], v[160:163], v[90:93]
	s_waitcnt lgkmcnt(1)
	v_mfma_f32_16x16x32_bf16 v[86:89], v[168:171], v[160:163], v[86:89]
	s_waitcnt lgkmcnt(0)
	v_mfma_f32_16x16x32_bf16 v[82:85], v[172:175], v[160:163], v[82:85]
	s_add_u32 m0, s20, 0x9000
	v_lshl_add_u64 v[206:207], v[190:191], 0, s[0:1]
	global_load_lds_dwordx4 v[206:207], off
	v_mfma_f32_16x16x32_bf16 v[78:81], v[152:155], v[164:167], v[78:81]
	v_mfma_f32_16x16x32_bf16 v[54:57], v[156:159], v[164:167], v[54:57]
	v_mfma_f32_16x16x32_bf16 v[38:41], v[168:171], v[164:167], v[38:41]
	s_add_u32 m0, s20, 0xa000
	v_lshl_add_u64 v[204:205], v[192:193], 0, s[0:1]
	global_load_lds_dwordx4 v[204:205], off
	v_mfma_f32_16x16x32_bf16 v[34:37], v[172:175], v[164:167], v[34:37]
	ds_read_b128 v[160:163], v110 offset:4096
	ds_read_b128 v[164:167], v111
	s_waitcnt lgkmcnt(1)
	v_mfma_f32_16x16x32_bf16 v[74:77], v[152:155], v[160:163], v[74:77]
	v_mfma_f32_16x16x32_bf16 v[70:73], v[156:159], v[160:163], v[70:73]
	s_add_u32 m0, s20, 0xb000
	v_lshl_add_u64 v[206:207], v[194:195], 0, s[0:1]
	global_load_lds_dwordx4 v[206:207], off
	v_mfma_f32_16x16x32_bf16 v[66:69], v[168:171], v[160:163], v[66:69]
	v_mfma_f32_16x16x32_bf16 v[62:65], v[172:175], v[160:163], v[62:65]
	s_waitcnt lgkmcnt(0)
	v_mfma_f32_16x16x32_bf16 v[58:61], v[152:155], v[164:167], v[58:61]
	s_add_u32 m0, s20, 0xc000
	v_lshl_add_u64 v[204:205], v[196:197], 0, s[0:1]
	global_load_lds_dwordx4 v[204:205], off
	ds_read_b128 v[152:155], v116 offset:16384
	v_mfma_f32_16x16x32_bf16 v[50:53], v[156:159], v[164:167], v[50:53]
	v_mfma_f32_16x16x32_bf16 v[46:49], v[168:171], v[164:167], v[46:49]
	v_mfma_f32_16x16x32_bf16 v[42:45], v[172:175], v[164:167], v[42:45]
	s_add_u32 m0, s20, 0xd000
	v_lshl_add_u64 v[206:207], v[198:199], 0, s[0:1]
	global_load_lds_dwordx4 v[206:207], off
	ds_read_b128 v[156:159], v116 offset:18432
	ds_read_b128 v[160:163], v114
	ds_read_b128 v[164:167], v114 offset:2048
	ds_read_b128 v[168:171], v116 offset:20480
	ds_read_b128 v[172:175], v117 offset:16384
	s_waitcnt lgkmcnt(3)
	v_mfma_f32_16x16x32_bf16 v[94:97], v[152:155], v[160:163], v[94:97]
	v_mfma_f32_16x16x32_bf16 v[90:93], v[156:159], v[160:163], v[90:93]
	s_waitcnt lgkmcnt(1)
	v_mfma_f32_16x16x32_bf16 v[86:89], v[168:171], v[160:163], v[86:89]
	s_add_u32 m0, s20, 0xe000
	v_lshl_add_u64 v[204:205], v[200:201], 0, s[0:1]
	global_load_lds_dwordx4 v[204:205], off
	s_waitcnt lgkmcnt(0)
	v_mfma_f32_16x16x32_bf16 v[82:85], v[172:175], v[160:163], v[82:85]
	v_mfma_f32_16x16x32_bf16 v[78:81], v[152:155], v[164:167], v[78:81]
	v_mfma_f32_16x16x32_bf16 v[54:57], v[156:159], v[164:167], v[54:57]
	s_add_u32 m0, s20, 0xf000
	v_lshl_add_u64 v[206:207], v[202:203], 0, s[0:1]
	global_load_lds_dwordx4 v[206:207], off
	v_mfma_f32_16x16x32_bf16 v[38:41], v[168:171], v[164:167], v[38:41]
	v_mfma_f32_16x16x32_bf16 v[34:37], v[172:175], v[164:167], v[34:37]
	ds_read_b128 v[160:163], v114 offset:4096
	ds_read_b128 v[164:167], v115
	s_waitcnt lgkmcnt(1)
	v_mfma_f32_16x16x32_bf16 v[74:77], v[152:155], v[160:163], v[74:77]
	v_mfma_f32_16x16x32_bf16 v[70:73], v[156:159], v[160:163], v[70:73]
	v_mfma_f32_16x16x32_bf16 v[66:69], v[168:171], v[160:163], v[66:69]
	v_mfma_f32_16x16x32_bf16 v[62:65], v[172:175], v[160:163], v[62:65]
	s_waitcnt lgkmcnt(0)
	v_mfma_f32_16x16x32_bf16 v[58:61], v[152:155], v[164:167], v[58:61]
	v_mfma_f32_16x16x32_bf16 v[50:53], v[156:159], v[164:167], v[50:53]
	v_mfma_f32_16x16x32_bf16 v[46:49], v[168:171], v[164:167], v[46:49]
	v_mfma_f32_16x16x32_bf16 v[42:45], v[172:175], v[164:167], v[42:45]
	s_setprio 0
	s_waitcnt vmcnt(0)
	s_barrier
	s_add_i32 s0, s19, 0x80
	s_min_u32 s0, s0, 0x3c0
	s_lshl_b32 s0, s0, 1
	s_setprio 1
	ds_read_b128 v[152:155], v112 offset:49152
	ds_read_b128 v[156:159], v112 offset:51200
	ds_read_b128 v[160:163], v110 offset:32768
	ds_read_b128 v[164:167], v110 offset:34816
	ds_read_b128 v[168:171], v112 offset:53248
	ds_read_b128 v[172:175], v113 offset:49152
	s_waitcnt lgkmcnt(3)
	v_mfma_f32_16x16x32_bf16 v[94:97], v[152:155], v[160:163], v[94:97]
	s_add_u32 m0, s20, 0x0
	v_lshl_add_u64 v[204:205], v[188:189], 0, s[0:1]
	global_load_lds_dwordx4 v[204:205], off
	v_mfma_f32_16x16x32_bf16 v[90:93], v[156:159], v[160:163], v[90:93]
	s_waitcnt lgkmcnt(1)
	v_mfma_f32_16x16x32_bf16 v[86:89], v[168:171], v[160:163], v[86:89]
	s_waitcnt lgkmcnt(0)
	v_mfma_f32_16x16x32_bf16 v[82:85], v[172:175], v[160:163], v[82:85]
	s_add_u32 m0, s20, 0x1000
	v_lshl_add_u64 v[206:207], v[190:191], 0, s[0:1]
	global_load_lds_dwordx4 v[206:207], off
	v_mfma_f32_16x16x32_bf16 v[78:81], v[152:155], v[164:167], v[78:81]
	v_mfma_f32_16x16x32_bf16 v[54:57], v[156:159], v[164:167], v[54:57]
	v_mfma_f32_16x16x32_bf16 v[38:41], v[168:171], v[164:167], v[38:41]
	s_add_u32 m0, s20, 0x2000
	v_lshl_add_u64 v[204:205], v[192:193], 0, s[0:1]
	global_load_lds_dwordx4 v[204:205], off
	v_mfma_f32_16x16x32_bf16 v[34:37], v[172:175], v[164:167], v[34:37]
	ds_read_b128 v[160:163], v110 offset:36864
	ds_read_b128 v[164:167], v111 offset:32768
	s_waitcnt lgkmcnt(1)
	v_mfma_f32_16x16x32_bf16 v[74:77], v[152:155], v[160:163], v[74:77]
	v_mfma_f32_16x16x32_bf16 v[70:73], v[156:159], v[160:163], v[70:73]
	s_add_u32 m0, s20, 0x3000
	v_lshl_add_u64 v[206:207], v[194:195], 0, s[0:1]
	global_load_lds_dwordx4 v[206:207], off
	v_mfma_f32_16x16x32_bf16 v[66:69], v[168:171], v[160:163], v[66:69]
	v_mfma_f32_16x16x32_bf16 v[62:65], v[172:175], v[160:163], v[62:65]
	s_waitcnt lgkmcnt(0)
	v_mfma_f32_16x16x32_bf16 v[58:61], v[152:155], v[164:167], v[58:61]
	s_add_u32 m0, s20, 0x4000
	v_lshl_add_u64 v[204:205], v[196:197], 0, s[0:1]
	global_load_lds_dwordx4 v[204:205], off
	ds_read_b128 v[152:155], v116 offset:49152
	v_mfma_f32_16x16x32_bf16 v[50:53], v[156:159], v[164:167], v[50:53]
	v_mfma_f32_16x16x32_bf16 v[46:49], v[168:171], v[164:167], v[46:49]
	v_mfma_f32_16x16x32_bf16 v[42:45], v[172:175], v[164:167], v[42:45]
	s_add_u32 m0, s20, 0x5000
	v_lshl_add_u64 v[206:207], v[198:199], 0, s[0:1]
	global_load_lds_dwordx4 v[206:207], off
	ds_read_b128 v[156:159], v116 offset:51200
	ds_read_b128 v[160:163], v114 offset:32768
	ds_read_b128 v[164:167], v114 offset:34816
	ds_read_b128 v[168:171], v116 offset:53248
	ds_read_b128 v[172:175], v117 offset:49152
	s_waitcnt lgkmcnt(3)
	v_mfma_f32_16x16x32_bf16 v[94:97], v[152:155], v[160:163], v[94:97]
	v_mfma_f32_16x16x32_bf16 v[90:93], v[156:159], v[160:163], v[90:93]
	s_waitcnt lgkmcnt(1)
	v_mfma_f32_16x16x32_bf16 v[86:89], v[168:171], v[160:163], v[86:89]
	s_add_u32 m0, s20, 0x6000
	v_lshl_add_u64 v[204:205], v[200:201], 0, s[0:1]
	global_load_lds_dwordx4 v[204:205], off
	s_waitcnt lgkmcnt(0)
	v_mfma_f32_16x16x32_bf16 v[82:85], v[172:175], v[160:163], v[82:85]
	v_mfma_f32_16x16x32_bf16 v[78:81], v[152:155], v[164:167], v[78:81]
	v_mfma_f32_16x16x32_bf16 v[54:57], v[156:159], v[164:167], v[54:57]
	s_add_u32 m0, s20, 0x7000
	v_lshl_add_u64 v[206:207], v[202:203], 0, s[0:1]
	global_load_lds_dwordx4 v[206:207], off
	v_mfma_f32_16x16x32_bf16 v[38:41], v[168:171], v[164:167], v[38:41]
	v_mfma_f32_16x16x32_bf16 v[34:37], v[172:175], v[164:167], v[34:37]
	ds_read_b128 v[160:163], v114 offset:36864
	ds_read_b128 v[164:167], v115 offset:32768
	s_waitcnt lgkmcnt(1)
	v_mfma_f32_16x16x32_bf16 v[74:77], v[152:155], v[160:163], v[74:77]
	v_mfma_f32_16x16x32_bf16 v[70:73], v[156:159], v[160:163], v[70:73]
	v_mfma_f32_16x16x32_bf16 v[66:69], v[168:171], v[160:163], v[66:69]
	v_mfma_f32_16x16x32_bf16 v[62:65], v[172:175], v[160:163], v[62:65]
	s_waitcnt lgkmcnt(0)
	v_mfma_f32_16x16x32_bf16 v[58:61], v[152:155], v[164:167], v[58:61]
	v_mfma_f32_16x16x32_bf16 v[50:53], v[156:159], v[164:167], v[50:53]
	v_mfma_f32_16x16x32_bf16 v[46:49], v[168:171], v[164:167], v[46:49]
	v_mfma_f32_16x16x32_bf16 v[42:45], v[172:175], v[164:167], v[42:45]
	s_setprio 0
	s_add_i32 s19, s19, 0x80
	s_add_i32 s18, s18, 2
	s_waitcnt vmcnt(0)
	s_barrier
	s_cmp_lt_u32 s18, 14
	s_cbranch_scc1 .Lglds_3547
	v_readlane_b32 s36, v254, 40
	s_lshl_b64 s[12:13], s[12:13], 21
	v_readlane_b32 s50, v254, 54
	v_readlane_b32 s51, v254, 55
	s_add_u32 s12, s50, s12
	s_addc_u32 s13, s51, s13
	s_waitcnt vmcnt(7)
	v_or_b32_e32 v4, s17, v119
	v_add_lshl_u32 v98, v118, s16, 10
	v_lshl_add_u64 v[2:3], s[12:13], 0, v[98:99]
	v_lshlrev_b32_e32 v98, 1, v4
	v_lshl_add_u64 v[4:5], v[2:3], 0, v[98:99]
	s_waitcnt vmcnt(6)
	v_cvt_pk_bf16_f32 v6, v94, v95
	v_cvt_pk_bf16_f32 v7, v96, v97
	global_store_dwordx2 v[4:5], v[6:7], off
	v_cvt_pk_bf16_f32 v6, v90, v91
	v_cvt_pk_bf16_f32 v7, v92, v93
	global_store_dwordx2 v[4:5], v[6:7], off offset:32
	v_cvt_pk_bf16_f32 v6, v86, v87
	v_cvt_pk_bf16_f32 v7, v88, v89
	global_store_dwordx2 v[4:5], v[6:7], off offset:64
	v_cvt_pk_bf16_f32 v6, v82, v83
	v_cvt_pk_bf16_f32 v7, v84, v85
	global_store_dwordx2 v[4:5], v[6:7], off offset:96
	v_lshl_add_u64 v[4:5], v[2:3], 0, s[4:5]
	v_lshl_add_u64 v[6:7], v[4:5], 0, v[98:99]
	v_cvt_pk_bf16_f32 v8, v78, v79
	v_cvt_pk_bf16_f32 v9, v80, v81
	global_store_dwordx2 v[6:7], v[8:9], off
	v_or_b32_e32 v6, 32, v98
	v_mov_b32_e32 v7, v99
	v_lshl_add_u64 v[8:9], v[4:5], 0, v[6:7]
	s_waitcnt vmcnt(10)
	v_cvt_pk_bf16_f32 v10, v54, v55
	v_cvt_pk_bf16_f32 v11, v56, v57
	global_store_dwordx2 v[8:9], v[10:11], off
	v_or_b32_e32 v8, 64, v98
	v_mov_b32_e32 v9, v99
	v_lshl_add_u64 v[10:11], v[4:5], 0, v[8:9]
	v_cvt_pk_bf16_f32 v12, v38, v39
	v_cvt_pk_bf16_f32 v13, v40, v41
	global_store_dwordx2 v[10:11], v[12:13], off
	v_or_b32_e32 v10, 0x60, v98
	v_mov_b32_e32 v11, v99
	v_lshl_add_u64 v[4:5], v[4:5], 0, v[10:11]
	v_cvt_pk_bf16_f32 v12, v34, v35
	v_cvt_pk_bf16_f32 v13, v36, v37
	global_store_dwordx2 v[4:5], v[12:13], off
	v_lshl_add_u64 v[4:5], v[2:3], 0, s[6:7]
	v_lshl_add_u64 v[12:13], v[4:5], 0, v[98:99]
	s_waitcnt vmcnt(11)
	v_cvt_pk_bf16_f32 v14, v74, v75
	v_cvt_pk_bf16_f32 v15, v76, v77
	global_store_dwordx2 v[12:13], v[14:15], off
	v_lshl_add_u64 v[12:13], v[4:5], 0, v[6:7]
	v_cvt_pk_bf16_f32 v14, v70, v71
	v_cvt_pk_bf16_f32 v15, v72, v73
	global_store_dwordx2 v[12:13], v[14:15], off
	v_lshl_add_u64 v[12:13], v[4:5], 0, v[8:9]
	v_cvt_pk_bf16_f32 v14, v66, v67
	v_cvt_pk_bf16_f32 v15, v68, v69
	global_store_dwordx2 v[12:13], v[14:15], off
	v_lshl_add_u64 v[4:5], v[4:5], 0, v[10:11]
	v_cvt_pk_bf16_f32 v12, v62, v63
	v_cvt_pk_bf16_f32 v13, v64, v65
	v_lshl_add_u64 v[2:3], v[2:3], 0, s[8:9]
	global_store_dwordx2 v[4:5], v[12:13], off
	v_lshl_add_u64 v[4:5], v[2:3], 0, v[98:99]
	v_cvt_pk_bf16_f32 v12, v58, v59
	v_cvt_pk_bf16_f32 v13, v60, v61
	global_store_dwordx2 v[4:5], v[12:13], off
	v_lshl_add_u64 v[4:5], v[2:3], 0, v[6:7]
	v_cvt_pk_bf16_f32 v6, v50, v51
	v_cvt_pk_bf16_f32 v7, v52, v53
	v_readlane_b32 s12, v254, 0
	global_store_dwordx2 v[4:5], v[6:7], off
	v_lshl_add_u64 v[4:5], v[2:3], 0, v[8:9]
	v_cvt_pk_bf16_f32 v6, v46, v47
	v_cvt_pk_bf16_f32 v7, v48, v49
	s_add_i32 s2, s2, s12
	v_readlane_b32 s37, v254, 41
	global_store_dwordx2 v[4:5], v[6:7], off
	v_lshl_add_u64 v[2:3], v[2:3], 0, v[10:11]
	v_cvt_pk_bf16_f32 v4, v42, v43
	v_cvt_pk_bf16_f32 v5, v44, v45
	s_cmpk_lt_i32 s2, 0x80
	v_readlane_b32 s38, v254, 42
	v_readlane_b32 s39, v254, 43
	v_readlane_b32 s40, v254, 44
	v_readlane_b32 s41, v254, 45
	v_readlane_b32 s42, v254, 46
	v_readlane_b32 s43, v254, 47
	v_readlane_b32 s44, v254, 48
	v_readlane_b32 s45, v254, 49
	v_readlane_b32 s46, v254, 50
	v_readlane_b32 s47, v254, 51
	v_readlane_b32 s48, v254, 52
	v_readlane_b32 s49, v254, 53
	v_readlane_b32 s13, v254, 1
	global_store_dwordx2 v[2:3], v[4:5], off
	s_cbranch_scc1 .LBB0_220

.Lglds_12468:
	s_add_i32 s4, s14, 0x40
	s_lshl_b32 s4, s4, 1
	s_setprio 1
	ds_read_b128 v[152:155], v112 offset:16384
	ds_read_b128 v[156:159], v112 offset:18432
	ds_read_b128 v[160:163], v110
	ds_read_b128 v[164:167], v110 offset:2048
	ds_read_b128 v[168:171], v112 offset:20480
	ds_read_b128 v[172:175], v113 offset:16384
	s_waitcnt lgkmcnt(3)
	v_mfma_f32_16x16x32_bf16 v[94:97], v[152:155], v[160:163], v[94:97]
	s_add_u32 m0, s15, 0x8000
	v_lshl_add_u64 v[200:201], v[184:185], 0, s[4:5]
	global_load_lds_dwordx4 v[200:201], off
	v_mfma_f32_16x16x32_bf16 v[90:93], v[156:159], v[160:163], v[90:93]
	s_waitcnt lgkmcnt(1)
	v_mfma_f32_16x16x32_bf16 v[86:89], v[168:171], v[160:163], v[86:89]
	s_waitcnt lgkmcnt(0)
	v_mfma_f32_16x16x32_bf16 v[82:85], v[172:175], v[160:163], v[82:85]
	s_add_u32 m0, s15, 0x9000
	v_lshl_add_u64 v[202:203], v[186:187], 0, s[4:5]
	global_load_lds_dwordx4 v[202:203], off
	v_mfma_f32_16x16x32_bf16 v[78:81], v[152:155], v[164:167], v[78:81]
	v_mfma_f32_16x16x32_bf16 v[74:77], v[156:159], v[164:167], v[74:77]
	v_mfma_f32_16x16x32_bf16 v[62:65], v[168:171], v[164:167], v[62:65]
	s_add_u32 m0, s15, 0xa000
	v_lshl_add_u64 v[200:201], v[188:189], 0, s[4:5]
	global_load_lds_dwordx4 v[200:201], off
	v_mfma_f32_16x16x32_bf16 v[30:33], v[172:175], v[164:167], v[30:33]
	ds_read_b128 v[160:163], v110 offset:4096
	ds_read_b128 v[164:167], v111
	s_waitcnt lgkmcnt(1)
	v_mfma_f32_16x16x32_bf16 v[66:69], v[152:155], v[160:163], v[66:69]
	v_mfma_f32_16x16x32_bf16 v[38:41], v[156:159], v[160:163], v[38:41]
	s_add_u32 m0, s15, 0xb000
	v_lshl_add_u64 v[202:203], v[190:191], 0, s[4:5]
	global_load_lds_dwordx4 v[202:203], off
	v_mfma_f32_16x16x32_bf16 v[34:37], v[168:171], v[160:163], v[34:37]
	v_mfma_f32_16x16x32_bf16 v[18:21], v[172:175], v[160:163], v[18:21]
	s_waitcnt lgkmcnt(0)
	v_mfma_f32_16x16x32_bf16 v[14:17], v[152:155], v[164:167], v[14:17]
	s_add_u32 m0, s15, 0xc000
	v_lshl_add_u64 v[200:201], v[192:193], 0, s[4:5]
	global_load_lds_dwordx4 v[200:201], off
	ds_read_b128 v[152:155], v116 offset:16384
	v_mfma_f32_16x16x32_bf16 v[10:13], v[156:159], v[164:167], v[10:13]
	v_mfma_f32_16x16x32_bf16 v[6:9], v[168:171], v[164:167], v[6:9]
	v_mfma_f32_16x16x32_bf16 v[2:5], v[172:175], v[164:167], v[2:5]
	s_add_u32 m0, s15, 0xd000
	v_lshl_add_u64 v[202:203], v[194:195], 0, s[4:5]
	global_load_lds_dwordx4 v[202:203], off
	ds_read_b128 v[156:159], v116 offset:18432
	ds_read_b128 v[160:163], v114
	ds_read_b128 v[164:167], v114 offset:2048
	ds_read_b128 v[168:171], v116 offset:20480
	ds_read_b128 v[172:175], v117 offset:16384
	s_waitcnt lgkmcnt(3)
	v_mfma_f32_16x16x32_bf16 v[94:97], v[152:155], v[160:163], v[94:97]
	v_mfma_f32_16x16x32_bf16 v[90:93], v[156:159], v[160:163], v[90:93]
	s_waitcnt lgkmcnt(1)
	v_mfma_f32_16x16x32_bf16 v[86:89], v[168:171], v[160:163], v[86:89]
	s_add_u32 m0, s15, 0xe000
	v_lshl_add_u64 v[200:201], v[196:197], 0, s[4:5]
	global_load_lds_dwordx4 v[200:201], off
	s_waitcnt lgkmcnt(0)
	v_mfma_f32_16x16x32_bf16 v[82:85], v[172:175], v[160:163], v[82:85]
	v_mfma_f32_16x16x32_bf16 v[78:81], v[152:155], v[164:167], v[78:81]
	v_mfma_f32_16x16x32_bf16 v[74:77], v[156:159], v[164:167], v[74:77]
	s_add_u32 m0, s15, 0xf000
	v_lshl_add_u64 v[202:203], v[198:199], 0, s[4:5]
	global_load_lds_dwordx4 v[202:203], off
	v_mfma_f32_16x16x32_bf16 v[62:65], v[168:171], v[164:167], v[62:65]
	v_mfma_f32_16x16x32_bf16 v[30:33], v[172:175], v[164:167], v[30:33]
	ds_read_b128 v[160:163], v114 offset:4096
	ds_read_b128 v[164:167], v115
	s_waitcnt lgkmcnt(1)
	v_mfma_f32_16x16x32_bf16 v[66:69], v[152:155], v[160:163], v[66:69]
	v_mfma_f32_16x16x32_bf16 v[38:41], v[156:159], v[160:163], v[38:41]
	v_mfma_f32_16x16x32_bf16 v[34:37], v[168:171], v[160:163], v[34:37]
	v_mfma_f32_16x16x32_bf16 v[18:21], v[172:175], v[160:163], v[18:21]
	s_waitcnt lgkmcnt(0)
	v_mfma_f32_16x16x32_bf16 v[14:17], v[152:155], v[164:167], v[14:17]
	v_mfma_f32_16x16x32_bf16 v[10:13], v[156:159], v[164:167], v[10:13]
	v_mfma_f32_16x16x32_bf16 v[6:9], v[168:171], v[164:167], v[6:9]
	v_mfma_f32_16x16x32_bf16 v[2:5], v[172:175], v[164:167], v[2:5]
	s_setprio 0
	s_waitcnt vmcnt(0)
	s_barrier
	s_add_i32 s4, s14, 0x80
	s_min_u32 s4, s4, 0x3c0
	s_lshl_b32 s4, s4, 1
	s_setprio 1
	ds_read_b128 v[152:155], v112 offset:49152
	ds_read_b128 v[156:159], v112 offset:51200
	ds_read_b128 v[160:163], v110 offset:32768
	ds_read_b128 v[164:167], v110 offset:34816
	ds_read_b128 v[168:171], v112 offset:53248
	ds_read_b128 v[172:175], v113 offset:49152
	s_waitcnt lgkmcnt(3)
	v_mfma_f32_16x16x32_bf16 v[94:97], v[152:155], v[160:163], v[94:97]
	s_add_u32 m0, s15, 0x0
	v_lshl_add_u64 v[200:201], v[184:185], 0, s[4:5]
	global_load_lds_dwordx4 v[200:201], off
	v_mfma_f32_16x16x32_bf16 v[90:93], v[156:159], v[160:163], v[90:93]
	s_waitcnt lgkmcnt(1)
	v_mfma_f32_16x16x32_bf16 v[86:89], v[168:171], v[160:163], v[86:89]
	s_waitcnt lgkmcnt(0)
	v_mfma_f32_16x16x32_bf16 v[82:85], v[172:175], v[160:163], v[82:85]
	s_add_u32 m0, s15, 0x1000
	v_lshl_add_u64 v[202:203], v[186:187], 0, s[4:5]
	global_load_lds_dwordx4 v[202:203], off
	v_mfma_f32_16x16x32_bf16 v[78:81], v[152:155], v[164:167], v[78:81]
	v_mfma_f32_16x16x32_bf16 v[74:77], v[156:159], v[164:167], v[74:77]
	v_mfma_f32_16x16x32_bf16 v[62:65], v[168:171], v[164:167], v[62:65]
	s_add_u32 m0, s15, 0x2000
	v_lshl_add_u64 v[200:201], v[188:189], 0, s[4:5]
	global_load_lds_dwordx4 v[200:201], off
	v_mfma_f32_16x16x32_bf16 v[30:33], v[172:175], v[164:167], v[30:33]
	ds_read_b128 v[160:163], v110 offset:36864
	ds_read_b128 v[164:167], v111 offset:32768
	s_waitcnt lgkmcnt(1)
	v_mfma_f32_16x16x32_bf16 v[66:69], v[152:155], v[160:163], v[66:69]
	v_mfma_f32_16x16x32_bf16 v[38:41], v[156:159], v[160:163], v[38:41]
	s_add_u32 m0, s15, 0x3000
	v_lshl_add_u64 v[202:203], v[190:191], 0, s[4:5]
	global_load_lds_dwordx4 v[202:203], off
	v_mfma_f32_16x16x32_bf16 v[34:37], v[168:171], v[160:163], v[34:37]
	v_mfma_f32_16x16x32_bf16 v[18:21], v[172:175], v[160:163], v[18:21]
	s_waitcnt lgkmcnt(0)
	v_mfma_f32_16x16x32_bf16 v[14:17], v[152:155], v[164:167], v[14:17]
	s_add_u32 m0, s15, 0x4000
	v_lshl_add_u64 v[200:201], v[192:193], 0, s[4:5]
	global_load_lds_dwordx4 v[200:201], off
	ds_read_b128 v[152:155], v116 offset:49152
	v_mfma_f32_16x16x32_bf16 v[10:13], v[156:159], v[164:167], v[10:13]
	v_mfma_f32_16x16x32_bf16 v[6:9], v[168:171], v[164:167], v[6:9]
	v_mfma_f32_16x16x32_bf16 v[2:5], v[172:175], v[164:167], v[2:5]
	s_add_u32 m0, s15, 0x5000
	v_lshl_add_u64 v[202:203], v[194:195], 0, s[4:5]
	global_load_lds_dwordx4 v[202:203], off
	ds_read_b128 v[156:159], v116 offset:51200
	ds_read_b128 v[160:163], v114 offset:32768
	ds_read_b128 v[164:167], v114 offset:34816
	ds_read_b128 v[168:171], v116 offset:53248
	ds_read_b128 v[172:175], v117 offset:49152
	s_waitcnt lgkmcnt(3)
	v_mfma_f32_16x16x32_bf16 v[94:97], v[152:155], v[160:163], v[94:97]
	v_mfma_f32_16x16x32_bf16 v[90:93], v[156:159], v[160:163], v[90:93]
	s_waitcnt lgkmcnt(1)
	v_mfma_f32_16x16x32_bf16 v[86:89], v[168:171], v[160:163], v[86:89]
	s_add_u32 m0, s15, 0x6000
	v_lshl_add_u64 v[200:201], v[196:197], 0, s[4:5]
	global_load_lds_dwordx4 v[200:201], off
	s_waitcnt lgkmcnt(0)
	v_mfma_f32_16x16x32_bf16 v[82:85], v[172:175], v[160:163], v[82:85]
	v_mfma_f32_16x16x32_bf16 v[78:81], v[152:155], v[164:167], v[78:81]
	v_mfma_f32_16x16x32_bf16 v[74:77], v[156:159], v[164:167], v[74:77]
	s_add_u32 m0, s15, 0x7000
	v_lshl_add_u64 v[202:203], v[198:199], 0, s[4:5]
	global_load_lds_dwordx4 v[202:203], off
	v_mfma_f32_16x16x32_bf16 v[62:65], v[168:171], v[164:167], v[62:65]
	v_mfma_f32_16x16x32_bf16 v[30:33], v[172:175], v[164:167], v[30:33]
	ds_read_b128 v[160:163], v114 offset:36864
	ds_read_b128 v[164:167], v115 offset:32768
	s_waitcnt lgkmcnt(1)
	v_mfma_f32_16x16x32_bf16 v[66:69], v[152:155], v[160:163], v[66:69]
	v_mfma_f32_16x16x32_bf16 v[38:41], v[156:159], v[160:163], v[38:41]
	v_mfma_f32_16x16x32_bf16 v[34:37], v[168:171], v[160:163], v[34:37]
	v_mfma_f32_16x16x32_bf16 v[18:21], v[172:175], v[160:163], v[18:21]
	s_waitcnt lgkmcnt(0)
	v_mfma_f32_16x16x32_bf16 v[14:17], v[152:155], v[164:167], v[14:17]
	v_mfma_f32_16x16x32_bf16 v[10:13], v[156:159], v[164:167], v[10:13]
	v_mfma_f32_16x16x32_bf16 v[6:9], v[168:171], v[164:167], v[6:9]
	v_mfma_f32_16x16x32_bf16 v[2:5], v[172:175], v[164:167], v[2:5]
	s_setprio 0
	s_add_i32 s14, s14, 0x80
	s_add_i32 s13, s13, 2
	s_waitcnt vmcnt(0)
	s_barrier
	s_cmp_lt_u32 s13, 14
	s_cbranch_scc1 .Lglds_12468
	s_waitcnt vmcnt(0)
	v_or_b32_e32 v170, s12, v119
	v_add_lshl_u32 v98, v118, s11, 10
	v_readlane_b32 s12, v254, 8
	v_readlane_b32 s13, v254, 9
	v_readlane_b32 s14, v254, 10
	v_readlane_b32 s15, v254, 11
	v_readlane_b32 s16, v254, 12
	v_readlane_b32 s17, v254, 13
	v_readlane_b32 s18, v254, 14
	v_readlane_b32 s19, v254, 15
	v_readlane_b32 s20, v254, 16
	v_readlane_b32 s21, v254, 17
	v_readlane_b32 s22, v254, 18
	v_readlane_b32 s23, v254, 19
	v_readlane_b32 s24, v254, 20
	v_readlane_b32 s25, v254, 21
	v_readlane_b32 s26, v254, 22
	v_readlane_b32 s27, v254, 23
	v_lshlrev_b32_e32 v168, 2, v170
	v_mov_b32_e32 v169, v99
	v_lshlrev_b64 v[174:175], 2, v[98:99]
	v_lshl_add_u64 v[152:153], s[12:13], 0, v[174:175]
	v_lshl_add_u64 v[160:161], s[82:83], 0, v[174:175]
	v_lshl_add_u64 v[152:153], v[152:153], 0, v[168:169]
	v_lshl_add_u64 v[160:161], v[160:161], 0, v[168:169]
	global_load_dwordx4 v[120:123], v[152:153], off
	global_load_dwordx4 v[124:127], v[152:153], off offset:64
	global_load_dwordx4 v[128:131], v[152:153], off offset:128
	global_load_dwordx4 v[132:135], v[152:153], off offset:192
	v_or_b32_e32 v172, 0x4000, v98
	v_mov_b32_e32 v173, v99
	v_lshlrev_b64 v[174:175], 2, v[172:173]
	v_lshl_add_u64 v[154:155], s[12:13], 0, v[174:175]
	v_lshl_add_u64 v[162:163], s[82:83], 0, v[174:175]
	v_lshl_add_u64 v[154:155], v[154:155], 0, v[168:169]
	v_lshl_add_u64 v[162:163], v[162:163], 0, v[168:169]
	global_load_dwordx4 v[136:139], v[154:155], off
	global_load_dwordx4 v[140:143], v[154:155], off offset:64
	global_load_dwordx4 v[144:147], v[154:155], off offset:128
	global_load_dwordx4 v[148:151], v[154:155], off offset:192
	v_or_b32_e32 v172, 0x8000, v98
	v_mov_b32_e32 v173, v99
	v_lshlrev_b64 v[174:175], 2, v[172:173]
	v_lshl_add_u64 v[156:157], s[12:13], 0, v[174:175]
	v_lshl_add_u64 v[164:165], s[82:83], 0, v[174:175]
	v_lshl_add_u64 v[156:157], v[156:157], 0, v[168:169]
	v_lshl_add_u64 v[164:165], v[164:165], 0, v[168:169]
	global_load_dwordx4 v[22:25], v[156:157], off
	global_load_dwordx4 v[26:29], v[156:157], off offset:64
	global_load_dwordx4 v[42:45], v[156:157], off offset:128
	global_load_dwordx4 v[46:49], v[156:157], off offset:192
	v_or_b32_e32 v172, 0xc000, v98
	v_mov_b32_e32 v173, v99
	v_lshlrev_b64 v[174:175], 2, v[172:173]
	v_lshl_add_u64 v[158:159], s[12:13], 0, v[174:175]
	v_lshl_add_u64 v[166:167], s[82:83], 0, v[174:175]
	v_lshl_add_u64 v[158:159], v[158:159], 0, v[168:169]
	v_lshl_add_u64 v[166:167], v[166:167], 0, v[168:169]
	global_load_dwordx4 v[50:53], v[158:159], off
	global_load_dwordx4 v[54:57], v[158:159], off offset:64
	global_load_dwordx4 v[58:61], v[158:159], off offset:128
	global_load_dwordx4 v[70:73], v[158:159], off offset:192
	s_waitcnt vmcnt(15)
	v_pk_fma_f32 v[120:121], v[120:121], s[6:7], v[94:95] op_sel_hi:[1,0,1]
	v_pk_fma_f32 v[122:123], v[122:123], s[6:7], v[96:97] op_sel_hi:[1,0,1]
	s_waitcnt vmcnt(14)
	v_pk_fma_f32 v[124:125], v[124:125], s[6:7], v[90:91] op_sel_hi:[1,0,1]
	v_pk_fma_f32 v[126:127], v[126:127], s[6:7], v[92:93] op_sel_hi:[1,0,1]
	s_waitcnt vmcnt(13)
	v_pk_fma_f32 v[128:129], v[128:129], s[6:7], v[86:87] op_sel_hi:[1,0,1]
	v_pk_fma_f32 v[130:131], v[130:131], s[6:7], v[88:89] op_sel_hi:[1,0,1]
	s_waitcnt vmcnt(12)
	v_pk_fma_f32 v[132:133], v[132:133], s[6:7], v[82:83] op_sel_hi:[1,0,1]
	v_pk_fma_f32 v[134:135], v[134:135], s[6:7], v[84:85] op_sel_hi:[1,0,1]
	s_waitcnt vmcnt(11)
	v_pk_fma_f32 v[136:137], v[136:137], s[6:7], v[78:79] op_sel_hi:[1,0,1]
	v_pk_fma_f32 v[138:139], v[138:139], s[6:7], v[80:81] op_sel_hi:[1,0,1]
	s_waitcnt vmcnt(10)
	v_pk_fma_f32 v[140:141], v[140:141], s[6:7], v[74:75] op_sel_hi:[1,0,1]
	v_pk_fma_f32 v[142:143], v[142:143], s[6:7], v[76:77] op_sel_hi:[1,0,1]
	s_waitcnt vmcnt(9)
	v_pk_fma_f32 v[144:145], v[144:145], s[6:7], v[62:63] op_sel_hi:[1,0,1]
	v_pk_fma_f32 v[146:147], v[146:147], s[6:7], v[64:65] op_sel_hi:[1,0,1]
	s_waitcnt vmcnt(8)
	v_pk_fma_f32 v[148:149], v[148:149], s[6:7], v[30:31] op_sel_hi:[1,0,1]
	v_pk_fma_f32 v[150:151], v[150:151], s[6:7], v[32:33] op_sel_hi:[1,0,1]
	s_waitcnt vmcnt(7)
	v_pk_fma_f32 v[22:23], v[22:23], s[6:7], v[66:67] op_sel_hi:[1,0,1]
	v_pk_fma_f32 v[24:25], v[24:25], s[6:7], v[68:69] op_sel_hi:[1,0,1]
	s_waitcnt vmcnt(6)
	v_pk_fma_f32 v[26:27], v[26:27], s[6:7], v[38:39] op_sel_hi:[1,0,1]
	v_pk_fma_f32 v[28:29], v[28:29], s[6:7], v[40:41] op_sel_hi:[1,0,1]
	s_waitcnt vmcnt(5)
	v_pk_fma_f32 v[42:43], v[42:43], s[6:7], v[34:35] op_sel_hi:[1,0,1]
	v_pk_fma_f32 v[44:45], v[44:45], s[6:7], v[36:37] op_sel_hi:[1,0,1]
	s_waitcnt vmcnt(4)
	v_pk_fma_f32 v[46:47], v[46:47], s[6:7], v[18:19] op_sel_hi:[1,0,1]
	v_pk_fma_f32 v[48:49], v[48:49], s[6:7], v[20:21] op_sel_hi:[1,0,1]
	s_waitcnt vmcnt(3)
	v_pk_fma_f32 v[50:51], v[50:51], s[6:7], v[14:15] op_sel_hi:[1,0,1]
	v_pk_fma_f32 v[52:53], v[52:53], s[6:7], v[16:17] op_sel_hi:[1,0,1]
	s_waitcnt vmcnt(2)
	v_pk_fma_f32 v[54:55], v[54:55], s[6:7], v[10:11] op_sel_hi:[1,0,1]
	v_pk_fma_f32 v[56:57], v[56:57], s[6:7], v[12:13] op_sel_hi:[1,0,1]
	s_waitcnt vmcnt(1)
	v_pk_fma_f32 v[58:59], v[58:59], s[6:7], v[6:7] op_sel_hi:[1,0,1]
	v_pk_fma_f32 v[60:61], v[60:61], s[6:7], v[8:9] op_sel_hi:[1,0,1]
	s_waitcnt vmcnt(0)
	v_pk_fma_f32 v[70:71], v[70:71], s[6:7], v[2:3] op_sel_hi:[1,0,1]
	v_pk_fma_f32 v[72:73], v[72:73], s[6:7], v[4:5] op_sel_hi:[1,0,1]
	global_store_dwordx4 v[160:161], v[120:123], off
	global_store_dwordx4 v[160:161], v[124:127], off offset:64
	global_store_dwordx4 v[160:161], v[128:131], off offset:128
	global_store_dwordx4 v[160:161], v[132:135], off offset:192
	global_store_dwordx4 v[162:163], v[136:139], off
	global_store_dwordx4 v[162:163], v[140:143], off offset:64
	global_store_dwordx4 v[162:163], v[144:147], off offset:128
	global_store_dwordx4 v[162:163], v[148:151], off offset:192
	global_store_dwordx4 v[164:165], v[22:25], off
	global_store_dwordx4 v[164:165], v[26:29], off offset:64
	global_store_dwordx4 v[164:165], v[42:45], off offset:128
	global_store_dwordx4 v[164:165], v[46:49], off offset:192
	global_store_dwordx4 v[166:167], v[50:53], off
	global_store_dwordx4 v[166:167], v[54:57], off offset:64
	global_store_dwordx4 v[166:167], v[58:61], off offset:128
	global_store_dwordx4 v[166:167], v[70:73], off offset:192
	s_add_i32 s7, s7, s3
	s_cmpk_lt_u32 s7, 0x100
	s_cbranch_scc1 .LBB0_422

.Lglds_14401:
	s_add_i32 s4, s13, 0x40
	s_lshl_b32 s4, s4, 1
	s_setprio 1
	ds_read_b128 v[152:155], v112 offset:16384
	ds_read_b128 v[156:159], v112 offset:18432
	ds_read_b128 v[160:163], v110
	ds_read_b128 v[164:167], v110 offset:2048
	ds_read_b128 v[168:171], v112 offset:20480
	ds_read_b128 v[172:175], v113 offset:16384
	s_waitcnt lgkmcnt(3)
	v_mfma_i32_16x16x64_i8 v[94:97], v[152:155], v[160:163], v[94:97]
	s_add_u32 m0, s14, 0x8000
	v_lshl_add_u64 v[200:201], v[184:185], 0, s[4:5]
	global_load_lds_dwordx4 v[200:201], off
	v_mfma_i32_16x16x64_i8 v[90:93], v[156:159], v[160:163], v[90:93]
	s_waitcnt lgkmcnt(1)
	v_mfma_i32_16x16x64_i8 v[86:89], v[168:171], v[160:163], v[86:89]
	s_waitcnt lgkmcnt(0)
	v_mfma_i32_16x16x64_i8 v[82:85], v[172:175], v[160:163], v[82:85]
	s_add_u32 m0, s14, 0x9000
	v_lshl_add_u64 v[202:203], v[186:187], 0, s[4:5]
	global_load_lds_dwordx4 v[202:203], off
	v_mfma_i32_16x16x64_i8 v[74:77], v[152:155], v[164:167], v[74:77]
	v_mfma_i32_16x16x64_i8 v[50:53], v[156:159], v[164:167], v[50:53]
	v_mfma_i32_16x16x64_i8 v[38:41], v[168:171], v[164:167], v[38:41]
	s_add_u32 m0, s14, 0xa000
	v_lshl_add_u64 v[200:201], v[188:189], 0, s[4:5]
	global_load_lds_dwordx4 v[200:201], off
	v_mfma_i32_16x16x64_i8 v[30:33], v[172:175], v[164:167], v[30:33]
	ds_read_b128 v[160:163], v110 offset:4096
	ds_read_b128 v[164:167], v111
	s_waitcnt lgkmcnt(1)
	v_mfma_i32_16x16x64_i8 v[34:37], v[152:155], v[160:163], v[34:37]
	v_mfma_i32_16x16x64_i8 v[26:29], v[156:159], v[160:163], v[26:29]
	s_add_u32 m0, s14, 0xb000
	v_lshl_add_u64 v[202:203], v[190:191], 0, s[4:5]
	global_load_lds_dwordx4 v[202:203], off
	v_mfma_i32_16x16x64_i8 v[22:25], v[168:171], v[160:163], v[22:25]
	v_mfma_i32_16x16x64_i8 v[18:21], v[172:175], v[160:163], v[18:21]
	s_waitcnt lgkmcnt(0)
	v_mfma_i32_16x16x64_i8 v[14:17], v[152:155], v[164:167], v[14:17]
	s_add_u32 m0, s14, 0xc000
	v_lshl_add_u64 v[200:201], v[192:193], 0, s[4:5]
	global_load_lds_dwordx4 v[200:201], off
	ds_read_b128 v[152:155], v116 offset:16384
	v_mfma_i32_16x16x64_i8 v[10:13], v[156:159], v[164:167], v[10:13]
	v_mfma_i32_16x16x64_i8 v[6:9], v[168:171], v[164:167], v[6:9]
	v_mfma_i32_16x16x64_i8 v[2:5], v[172:175], v[164:167], v[2:5]
	s_add_u32 m0, s14, 0xd000
	v_lshl_add_u64 v[202:203], v[194:195], 0, s[4:5]
	global_load_lds_dwordx4 v[202:203], off
	ds_read_b128 v[156:159], v116 offset:18432
	ds_read_b128 v[160:163], v114
	ds_read_b128 v[164:167], v114 offset:2048
	ds_read_b128 v[168:171], v116 offset:20480
	ds_read_b128 v[172:175], v117 offset:16384
	s_waitcnt lgkmcnt(3)
	v_mfma_i32_16x16x64_i8 v[94:97], v[152:155], v[160:163], v[94:97]
	v_mfma_i32_16x16x64_i8 v[90:93], v[156:159], v[160:163], v[90:93]
	s_waitcnt lgkmcnt(1)
	v_mfma_i32_16x16x64_i8 v[86:89], v[168:171], v[160:163], v[86:89]
	s_add_u32 m0, s14, 0xe000
	v_lshl_add_u64 v[200:201], v[196:197], 0, s[4:5]
	global_load_lds_dwordx4 v[200:201], off
	s_waitcnt lgkmcnt(0)
	v_mfma_i32_16x16x64_i8 v[82:85], v[172:175], v[160:163], v[82:85]
	v_mfma_i32_16x16x64_i8 v[74:77], v[152:155], v[164:167], v[74:77]
	v_mfma_i32_16x16x64_i8 v[50:53], v[156:159], v[164:167], v[50:53]
	s_add_u32 m0, s14, 0xf000
	v_lshl_add_u64 v[202:203], v[198:199], 0, s[4:5]
	global_load_lds_dwordx4 v[202:203], off
	v_mfma_i32_16x16x64_i8 v[38:41], v[168:171], v[164:167], v[38:41]
	v_mfma_i32_16x16x64_i8 v[30:33], v[172:175], v[164:167], v[30:33]
	ds_read_b128 v[160:163], v114 offset:4096
	ds_read_b128 v[164:167], v115
	s_waitcnt lgkmcnt(1)
	v_mfma_i32_16x16x64_i8 v[34:37], v[152:155], v[160:163], v[34:37]
	v_mfma_i32_16x16x64_i8 v[26:29], v[156:159], v[160:163], v[26:29]
	v_mfma_i32_16x16x64_i8 v[22:25], v[168:171], v[160:163], v[22:25]
	v_mfma_i32_16x16x64_i8 v[18:21], v[172:175], v[160:163], v[18:21]
	s_waitcnt lgkmcnt(0)
	v_mfma_i32_16x16x64_i8 v[14:17], v[152:155], v[164:167], v[14:17]
	v_mfma_i32_16x16x64_i8 v[10:13], v[156:159], v[164:167], v[10:13]
	v_mfma_i32_16x16x64_i8 v[6:9], v[168:171], v[164:167], v[6:9]
	v_mfma_i32_16x16x64_i8 v[2:5], v[172:175], v[164:167], v[2:5]
	s_setprio 0
	s_waitcnt vmcnt(0)
	s_barrier
	s_add_i32 s4, s13, 0x80
	s_min_u32 s4, s4, 0x1c0
	s_lshl_b32 s4, s4, 1
	s_setprio 1
	ds_read_b128 v[152:155], v112 offset:49152
	ds_read_b128 v[156:159], v112 offset:51200
	ds_read_b128 v[160:163], v110 offset:32768
	ds_read_b128 v[164:167], v110 offset:34816
	ds_read_b128 v[168:171], v112 offset:53248
	ds_read_b128 v[172:175], v113 offset:49152
	s_waitcnt lgkmcnt(3)
	v_mfma_i32_16x16x64_i8 v[94:97], v[152:155], v[160:163], v[94:97]
	s_add_u32 m0, s14, 0x0
	v_lshl_add_u64 v[200:201], v[184:185], 0, s[4:5]
	global_load_lds_dwordx4 v[200:201], off
	v_mfma_i32_16x16x64_i8 v[90:93], v[156:159], v[160:163], v[90:93]
	s_waitcnt lgkmcnt(1)
	v_mfma_i32_16x16x64_i8 v[86:89], v[168:171], v[160:163], v[86:89]
	s_waitcnt lgkmcnt(0)
	v_mfma_i32_16x16x64_i8 v[82:85], v[172:175], v[160:163], v[82:85]
	s_add_u32 m0, s14, 0x1000
	v_lshl_add_u64 v[202:203], v[186:187], 0, s[4:5]
	global_load_lds_dwordx4 v[202:203], off
	v_mfma_i32_16x16x64_i8 v[74:77], v[152:155], v[164:167], v[74:77]
	v_mfma_i32_16x16x64_i8 v[50:53], v[156:159], v[164:167], v[50:53]
	v_mfma_i32_16x16x64_i8 v[38:41], v[168:171], v[164:167], v[38:41]
	s_add_u32 m0, s14, 0x2000
	v_lshl_add_u64 v[200:201], v[188:189], 0, s[4:5]
	global_load_lds_dwordx4 v[200:201], off
	v_mfma_i32_16x16x64_i8 v[30:33], v[172:175], v[164:167], v[30:33]
	ds_read_b128 v[160:163], v110 offset:36864
	ds_read_b128 v[164:167], v111 offset:32768
	s_waitcnt lgkmcnt(1)
	v_mfma_i32_16x16x64_i8 v[34:37], v[152:155], v[160:163], v[34:37]
	v_mfma_i32_16x16x64_i8 v[26:29], v[156:159], v[160:163], v[26:29]
	s_add_u32 m0, s14, 0x3000
	v_lshl_add_u64 v[202:203], v[190:191], 0, s[4:5]
	global_load_lds_dwordx4 v[202:203], off
	v_mfma_i32_16x16x64_i8 v[22:25], v[168:171], v[160:163], v[22:25]
	v_mfma_i32_16x16x64_i8 v[18:21], v[172:175], v[160:163], v[18:21]
	s_waitcnt lgkmcnt(0)
	v_mfma_i32_16x16x64_i8 v[14:17], v[152:155], v[164:167], v[14:17]
	s_add_u32 m0, s14, 0x4000
	v_lshl_add_u64 v[200:201], v[192:193], 0, s[4:5]
	global_load_lds_dwordx4 v[200:201], off
	ds_read_b128 v[152:155], v116 offset:49152
	v_mfma_i32_16x16x64_i8 v[10:13], v[156:159], v[164:167], v[10:13]
	v_mfma_i32_16x16x64_i8 v[6:9], v[168:171], v[164:167], v[6:9]
	v_mfma_i32_16x16x64_i8 v[2:5], v[172:175], v[164:167], v[2:5]
	s_add_u32 m0, s14, 0x5000
	v_lshl_add_u64 v[202:203], v[194:195], 0, s[4:5]
	global_load_lds_dwordx4 v[202:203], off
	ds_read_b128 v[156:159], v116 offset:51200
	ds_read_b128 v[160:163], v114 offset:32768
	ds_read_b128 v[164:167], v114 offset:34816
	ds_read_b128 v[168:171], v116 offset:53248
	ds_read_b128 v[172:175], v117 offset:49152
	s_waitcnt lgkmcnt(3)
	v_mfma_i32_16x16x64_i8 v[94:97], v[152:155], v[160:163], v[94:97]
	v_mfma_i32_16x16x64_i8 v[90:93], v[156:159], v[160:163], v[90:93]
	s_waitcnt lgkmcnt(1)
	v_mfma_i32_16x16x64_i8 v[86:89], v[168:171], v[160:163], v[86:89]
	s_add_u32 m0, s14, 0x6000
	v_lshl_add_u64 v[200:201], v[196:197], 0, s[4:5]
	global_load_lds_dwordx4 v[200:201], off
	s_waitcnt lgkmcnt(0)
	v_mfma_i32_16x16x64_i8 v[82:85], v[172:175], v[160:163], v[82:85]
	v_mfma_i32_16x16x64_i8 v[74:77], v[152:155], v[164:167], v[74:77]
	v_mfma_i32_16x16x64_i8 v[50:53], v[156:159], v[164:167], v[50:53]
	s_add_u32 m0, s14, 0x7000
	v_lshl_add_u64 v[202:203], v[198:199], 0, s[4:5]
	global_load_lds_dwordx4 v[202:203], off
	v_mfma_i32_16x16x64_i8 v[38:41], v[168:171], v[164:167], v[38:41]
	v_mfma_i32_16x16x64_i8 v[30:33], v[172:175], v[164:167], v[30:33]
	ds_read_b128 v[160:163], v114 offset:36864
	ds_read_b128 v[164:167], v115 offset:32768
	s_waitcnt lgkmcnt(1)
	v_mfma_i32_16x16x64_i8 v[34:37], v[152:155], v[160:163], v[34:37]
	v_mfma_i32_16x16x64_i8 v[26:29], v[156:159], v[160:163], v[26:29]
	v_mfma_i32_16x16x64_i8 v[22:25], v[168:171], v[160:163], v[22:25]
	v_mfma_i32_16x16x64_i8 v[18:21], v[172:175], v[160:163], v[18:21]
	s_waitcnt lgkmcnt(0)
	v_mfma_i32_16x16x64_i8 v[14:17], v[152:155], v[164:167], v[14:17]
	v_mfma_i32_16x16x64_i8 v[10:13], v[156:159], v[164:167], v[10:13]
	v_mfma_i32_16x16x64_i8 v[6:9], v[168:171], v[164:167], v[6:9]
	v_mfma_i32_16x16x64_i8 v[2:5], v[172:175], v[164:167], v[2:5]
	s_setprio 0
	s_add_i32 s13, s13, 0x80
	s_add_i32 s12, s12, 2
	s_waitcnt vmcnt(0)
	s_barrier
	s_cmp_lt_u32 s12, 6
	s_cbranch_scc1 .Lglds_14401
	v_cvt_f32_i32_e32 v94, v94
	v_cvt_f32_i32_e32 v95, v95
	v_cvt_f32_i32_e32 v96, v96
	v_cvt_f32_i32_e32 v97, v97
	v_cvt_f32_i32_e32 v90, v90
	v_cvt_f32_i32_e32 v91, v91
	v_cvt_f32_i32_e32 v92, v92
	v_cvt_f32_i32_e32 v93, v93
	v_cvt_f32_i32_e32 v86, v86
	v_cvt_f32_i32_e32 v87, v87
	v_cvt_f32_i32_e32 v88, v88
	v_cvt_f32_i32_e32 v89, v89
	v_cvt_f32_i32_e32 v82, v82
	v_cvt_f32_i32_e32 v83, v83
	v_cvt_f32_i32_e32 v84, v84
	v_cvt_f32_i32_e32 v85, v85
	v_cvt_f32_i32_e32 v74, v74
	v_cvt_f32_i32_e32 v75, v75
	v_cvt_f32_i32_e32 v76, v76
	v_cvt_f32_i32_e32 v77, v77
	v_cvt_f32_i32_e32 v50, v50
	v_cvt_f32_i32_e32 v51, v51
	v_cvt_f32_i32_e32 v52, v52
	v_cvt_f32_i32_e32 v53, v53
	v_cvt_f32_i32_e32 v38, v38
	v_cvt_f32_i32_e32 v39, v39
	v_cvt_f32_i32_e32 v40, v40
	v_cvt_f32_i32_e32 v41, v41
	v_cvt_f32_i32_e32 v30, v30
	v_cvt_f32_i32_e32 v31, v31
	v_cvt_f32_i32_e32 v32, v32
	v_cvt_f32_i32_e32 v33, v33
	v_cvt_f32_i32_e32 v34, v34
	v_cvt_f32_i32_e32 v35, v35
	v_cvt_f32_i32_e32 v36, v36
	v_cvt_f32_i32_e32 v37, v37
	v_cvt_f32_i32_e32 v26, v26
	v_cvt_f32_i32_e32 v27, v27
	v_cvt_f32_i32_e32 v28, v28
	v_cvt_f32_i32_e32 v29, v29
	v_cvt_f32_i32_e32 v22, v22
	v_cvt_f32_i32_e32 v23, v23
	v_cvt_f32_i32_e32 v24, v24
	v_cvt_f32_i32_e32 v25, v25
	v_cvt_f32_i32_e32 v18, v18
	v_cvt_f32_i32_e32 v19, v19
	v_cvt_f32_i32_e32 v20, v20
	v_cvt_f32_i32_e32 v21, v21
	v_cvt_f32_i32_e32 v14, v14
	v_cvt_f32_i32_e32 v15, v15
	v_cvt_f32_i32_e32 v16, v16
	v_cvt_f32_i32_e32 v17, v17
	v_cvt_f32_i32_e32 v10, v10
	v_cvt_f32_i32_e32 v11, v11
	v_cvt_f32_i32_e32 v12, v12
	v_cvt_f32_i32_e32 v13, v13
	v_cvt_f32_i32_e32 v6, v6
	v_cvt_f32_i32_e32 v7, v7
	v_cvt_f32_i32_e32 v8, v8
	v_cvt_f32_i32_e32 v9, v9
	v_cvt_f32_i32_e32 v2, v2
	v_cvt_f32_i32_e32 v3, v3
	v_cvt_f32_i32_e32 v4, v4
	v_cvt_f32_i32_e32 v5, v5
	s_waitcnt vmcnt(0)
	v_add_u32_e32 v98, s10, v118
	v_or_b32_e32 v146, s11, v119
	v_lshl_add_u64 v[144:145], v[98:99], 2, s[68:69]
	v_lshlrev_b32_e32 v148, 2, v146
	global_load_dword v136, v[144:145], off
	global_load_dword v138, v[144:145], off offset:64
	global_load_dword v140, v[144:145], off offset:128
	global_load_dword v142, v[144:145], off offset:192
	global_load_dwordx4 v[120:123], v148, s[74:75]
	global_load_dwordx4 v[124:127], v148, s[74:75] offset:64
	global_load_dwordx4 v[128:131], v148, s[74:75] offset:128
	global_load_dwordx4 v[132:135], v148, s[74:75] offset:192
	v_lshlrev_b32_e32 v146, 1, v146
	v_mov_b32_e32 v147, v99
	v_lshlrev_b64 v[42:43], 12, v[98:99]
	v_lshl_add_u64 v[42:43], s[64:65], 0, v[42:43]
	v_lshl_add_u64 v[42:43], v[42:43], 0, v[146:147]
	v_or_b32_e32 v54, 16, v98
	v_mov_b32_e32 v55, v99
	v_lshlrev_b64 v[44:45], 12, v[54:55]
	v_lshl_add_u64 v[44:45], s[64:65], 0, v[44:45]
	v_lshl_add_u64 v[44:45], v[44:45], 0, v[146:147]
	v_or_b32_e32 v54, 32, v98
	v_mov_b32_e32 v55, v99
	v_lshlrev_b64 v[46:47], 12, v[54:55]
	v_lshl_add_u64 v[46:47], s[64:65], 0, v[46:47]
	v_lshl_add_u64 v[46:47], v[46:47], 0, v[146:147]
	v_or_b32_e32 v54, 48, v98
	v_mov_b32_e32 v55, v99
	v_lshlrev_b64 v[48:49], 12, v[54:55]
	v_lshl_add_u64 v[48:49], s[64:65], 0, v[48:49]
	v_lshl_add_u64 v[48:49], v[48:49], 0, v[146:147]
	s_waitcnt vmcnt(0)
	v_pk_mul_f32 v[94:95], v[136:137], v[94:95] op_sel_hi:[0,1]
	v_pk_mul_f32 v[96:97], v[136:137], v[96:97] op_sel_hi:[0,1]
	v_pk_mul_f32 v[94:95], v[120:121], v[94:95]
	v_pk_mul_f32 v[96:97], v[96:97], v[122:123]
	v_cvt_pk_bf16_f32 v94, v94, v95
	v_cvt_pk_bf16_f32 v95, v96, v97
	global_store_dwordx2 v[42:43], v[94:95], off
	v_pk_mul_f32 v[90:91], v[136:137], v[90:91] op_sel_hi:[0,1]
	v_pk_mul_f32 v[92:93], v[136:137], v[92:93] op_sel_hi:[0,1]
	v_pk_mul_f32 v[90:91], v[124:125], v[90:91]
	v_pk_mul_f32 v[92:93], v[92:93], v[126:127]
	v_cvt_pk_bf16_f32 v90, v90, v91
	v_cvt_pk_bf16_f32 v91, v92, v93
	global_store_dwordx2 v[42:43], v[90:91], off offset:32
	v_pk_mul_f32 v[86:87], v[136:137], v[86:87] op_sel_hi:[0,1]
	v_pk_mul_f32 v[88:89], v[136:137], v[88:89] op_sel_hi:[0,1]
	v_pk_mul_f32 v[86:87], v[128:129], v[86:87]
	v_pk_mul_f32 v[88:89], v[88:89], v[130:131]
	v_cvt_pk_bf16_f32 v86, v86, v87
	v_cvt_pk_bf16_f32 v87, v88, v89
	global_store_dwordx2 v[42:43], v[86:87], off offset:64
	v_pk_mul_f32 v[82:83], v[136:137], v[82:83] op_sel_hi:[0,1]
	v_pk_mul_f32 v[84:85], v[136:137], v[84:85] op_sel_hi:[0,1]
	v_pk_mul_f32 v[82:83], v[132:133], v[82:83]
	v_pk_mul_f32 v[84:85], v[84:85], v[134:135]
	v_cvt_pk_bf16_f32 v82, v82, v83
	v_cvt_pk_bf16_f32 v83, v84, v85
	global_store_dwordx2 v[42:43], v[82:83], off offset:96
	v_pk_mul_f32 v[74:75], v[138:139], v[74:75] op_sel_hi:[0,1]
	v_pk_mul_f32 v[76:77], v[138:139], v[76:77] op_sel_hi:[0,1]
	v_pk_mul_f32 v[74:75], v[120:121], v[74:75]
	v_pk_mul_f32 v[76:77], v[76:77], v[122:123]
	v_cvt_pk_bf16_f32 v74, v74, v75
	v_cvt_pk_bf16_f32 v75, v76, v77
	global_store_dwordx2 v[44:45], v[74:75], off
	v_pk_mul_f32 v[50:51], v[138:139], v[50:51] op_sel_hi:[0,1]
	v_pk_mul_f32 v[52:53], v[138:139], v[52:53] op_sel_hi:[0,1]
	v_pk_mul_f32 v[50:51], v[124:125], v[50:51]
	v_pk_mul_f32 v[52:53], v[52:53], v[126:127]
	v_cvt_pk_bf16_f32 v50, v50, v51
	v_cvt_pk_bf16_f32 v51, v52, v53
	global_store_dwordx2 v[44:45], v[50:51], off offset:32
	v_pk_mul_f32 v[38:39], v[138:139], v[38:39] op_sel_hi:[0,1]
	v_pk_mul_f32 v[40:41], v[138:139], v[40:41] op_sel_hi:[0,1]
	v_pk_mul_f32 v[38:39], v[128:129], v[38:39]
	v_pk_mul_f32 v[40:41], v[40:41], v[130:131]
	v_cvt_pk_bf16_f32 v38, v38, v39
	v_cvt_pk_bf16_f32 v39, v40, v41
	global_store_dwordx2 v[44:45], v[38:39], off offset:64
	v_pk_mul_f32 v[30:31], v[138:139], v[30:31] op_sel_hi:[0,1]
	v_pk_mul_f32 v[32:33], v[138:139], v[32:33] op_sel_hi:[0,1]
	v_pk_mul_f32 v[30:31], v[132:133], v[30:31]
	v_pk_mul_f32 v[32:33], v[32:33], v[134:135]
	v_cvt_pk_bf16_f32 v30, v30, v31
	v_cvt_pk_bf16_f32 v31, v32, v33
	global_store_dwordx2 v[44:45], v[30:31], off offset:96
	v_pk_mul_f32 v[34:35], v[140:141], v[34:35] op_sel_hi:[0,1]
	v_pk_mul_f32 v[36:37], v[140:141], v[36:37] op_sel_hi:[0,1]
	v_pk_mul_f32 v[34:35], v[120:121], v[34:35]
	v_pk_mul_f32 v[36:37], v[36:37], v[122:123]
	v_cvt_pk_bf16_f32 v34, v34, v35
	v_cvt_pk_bf16_f32 v35, v36, v37
	global_store_dwordx2 v[46:47], v[34:35], off
	v_pk_mul_f32 v[26:27], v[140:141], v[26:27] op_sel_hi:[0,1]
	v_pk_mul_f32 v[28:29], v[140:141], v[28:29] op_sel_hi:[0,1]
	v_pk_mul_f32 v[26:27], v[124:125], v[26:27]
	v_pk_mul_f32 v[28:29], v[28:29], v[126:127]
	v_cvt_pk_bf16_f32 v26, v26, v27
	v_cvt_pk_bf16_f32 v27, v28, v29
	global_store_dwordx2 v[46:47], v[26:27], off offset:32
	v_pk_mul_f32 v[22:23], v[140:141], v[22:23] op_sel_hi:[0,1]
	v_pk_mul_f32 v[24:25], v[140:141], v[24:25] op_sel_hi:[0,1]
	v_pk_mul_f32 v[22:23], v[128:129], v[22:23]
	v_pk_mul_f32 v[24:25], v[24:25], v[130:131]
	v_cvt_pk_bf16_f32 v22, v22, v23
	v_cvt_pk_bf16_f32 v23, v24, v25
	global_store_dwordx2 v[46:47], v[22:23], off offset:64
	v_pk_mul_f32 v[18:19], v[140:141], v[18:19] op_sel_hi:[0,1]
	v_pk_mul_f32 v[20:21], v[140:141], v[20:21] op_sel_hi:[0,1]
	v_pk_mul_f32 v[18:19], v[132:133], v[18:19]
	v_pk_mul_f32 v[20:21], v[20:21], v[134:135]
	v_cvt_pk_bf16_f32 v18, v18, v19
	v_cvt_pk_bf16_f32 v19, v20, v21
	global_store_dwordx2 v[46:47], v[18:19], off offset:96
	v_pk_mul_f32 v[14:15], v[142:143], v[14:15] op_sel_hi:[0,1]
	v_pk_mul_f32 v[16:17], v[142:143], v[16:17] op_sel_hi:[0,1]
	v_pk_mul_f32 v[14:15], v[120:121], v[14:15]
	v_pk_mul_f32 v[16:17], v[16:17], v[122:123]
	v_cvt_pk_bf16_f32 v14, v14, v15
	v_cvt_pk_bf16_f32 v15, v16, v17
	global_store_dwordx2 v[48:49], v[14:15], off
	v_pk_mul_f32 v[10:11], v[142:143], v[10:11] op_sel_hi:[0,1]
	v_pk_mul_f32 v[12:13], v[142:143], v[12:13] op_sel_hi:[0,1]
	v_pk_mul_f32 v[10:11], v[124:125], v[10:11]
	v_pk_mul_f32 v[12:13], v[12:13], v[126:127]
	v_cvt_pk_bf16_f32 v10, v10, v11
	v_cvt_pk_bf16_f32 v11, v12, v13
	global_store_dwordx2 v[48:49], v[10:11], off offset:32
	v_pk_mul_f32 v[6:7], v[142:143], v[6:7] op_sel_hi:[0,1]
	v_pk_mul_f32 v[8:9], v[142:143], v[8:9] op_sel_hi:[0,1]
	v_pk_mul_f32 v[6:7], v[128:129], v[6:7]
	v_pk_mul_f32 v[8:9], v[8:9], v[130:131]
	v_cvt_pk_bf16_f32 v6, v6, v7
	v_cvt_pk_bf16_f32 v7, v8, v9
	global_store_dwordx2 v[48:49], v[6:7], off offset:64
	v_pk_mul_f32 v[2:3], v[142:143], v[2:3] op_sel_hi:[0,1]
	v_pk_mul_f32 v[4:5], v[142:143], v[4:5] op_sel_hi:[0,1]
	v_pk_mul_f32 v[2:3], v[132:133], v[2:3]
	v_pk_mul_f32 v[4:5], v[4:5], v[134:135]
	v_cvt_pk_bf16_f32 v2, v2, v3
	v_cvt_pk_bf16_f32 v3, v4, v5
	global_store_dwordx2 v[48:49], v[2:3], off offset:96
	s_add_i32 s6, s6, s3
	s_cmpk_lt_u32 s6, 0x200
	s_cbranch_scc1 .LBB0_518

.Lglds_22142:
	s_add_i32 s4, s16, 0x40
	s_lshl_b32 s4, s4, 1
	s_setprio 1
	ds_read_b128 v[152:155], v112 offset:16384
	ds_read_b128 v[156:159], v112 offset:18432
	ds_read_b128 v[160:163], v110
	ds_read_b128 v[164:167], v110 offset:2048
	ds_read_b128 v[168:171], v112 offset:20480
	ds_read_b128 v[172:175], v113 offset:16384
	s_waitcnt lgkmcnt(3)
	v_mfma_f32_16x16x32_bf16 v[94:97], v[152:155], v[160:163], v[94:97]
	s_add_u32 m0, s17, 0x8000
	v_lshl_add_u64 v[204:205], v[188:189], 0, s[4:5]
	global_load_lds_dwordx4 v[204:205], off
	v_mfma_f32_16x16x32_bf16 v[90:93], v[156:159], v[160:163], v[90:93]
	s_waitcnt lgkmcnt(1)
	v_mfma_f32_16x16x32_bf16 v[86:89], v[168:171], v[160:163], v[86:89]
	s_waitcnt lgkmcnt(0)
	v_mfma_f32_16x16x32_bf16 v[82:85], v[172:175], v[160:163], v[82:85]
	s_add_u32 m0, s17, 0x9000
	v_lshl_add_u64 v[206:207], v[190:191], 0, s[4:5]
	global_load_lds_dwordx4 v[206:207], off
	v_mfma_f32_16x16x32_bf16 v[54:57], v[152:155], v[164:167], v[54:57]
	v_mfma_f32_16x16x32_bf16 v[42:45], v[156:159], v[164:167], v[42:45]
	v_mfma_f32_16x16x32_bf16 v[38:41], v[168:171], v[164:167], v[38:41]
	s_add_u32 m0, s17, 0xa000
	v_lshl_add_u64 v[204:205], v[192:193], 0, s[4:5]
	global_load_lds_dwordx4 v[204:205], off
	v_mfma_f32_16x16x32_bf16 v[34:37], v[172:175], v[164:167], v[34:37]
	ds_read_b128 v[160:163], v110 offset:4096
	ds_read_b128 v[164:167], v111
	s_waitcnt lgkmcnt(1)
	v_mfma_f32_16x16x32_bf16 v[78:81], v[152:155], v[160:163], v[78:81]
	v_mfma_f32_16x16x32_bf16 v[74:77], v[156:159], v[160:163], v[74:77]
	s_add_u32 m0, s17, 0xb000
	v_lshl_add_u64 v[206:207], v[194:195], 0, s[4:5]
	global_load_lds_dwordx4 v[206:207], off
	v_mfma_f32_16x16x32_bf16 v[70:73], v[168:171], v[160:163], v[70:73]
	v_mfma_f32_16x16x32_bf16 v[66:69], v[172:175], v[160:163], v[66:69]
	s_waitcnt lgkmcnt(0)
	v_mfma_f32_16x16x32_bf16 v[62:65], v[152:155], v[164:167], v[62:65]
	s_add_u32 m0, s17, 0xc000
	v_lshl_add_u64 v[204:205], v[196:197], 0, s[4:5]
	global_load_lds_dwordx4 v[204:205], off
	ds_read_b128 v[152:155], v116 offset:16384
	v_mfma_f32_16x16x32_bf16 v[58:61], v[156:159], v[164:167], v[58:61]
	v_mfma_f32_16x16x32_bf16 v[50:53], v[168:171], v[164:167], v[50:53]
	v_mfma_f32_16x16x32_bf16 v[46:49], v[172:175], v[164:167], v[46:49]
	s_add_u32 m0, s17, 0xd000
	v_lshl_add_u64 v[206:207], v[198:199], 0, s[4:5]
	global_load_lds_dwordx4 v[206:207], off
	ds_read_b128 v[156:159], v116 offset:18432
	ds_read_b128 v[160:163], v114
	ds_read_b128 v[164:167], v114 offset:2048
	ds_read_b128 v[168:171], v116 offset:20480
	ds_read_b128 v[172:175], v117 offset:16384
	s_waitcnt lgkmcnt(3)
	v_mfma_f32_16x16x32_bf16 v[94:97], v[152:155], v[160:163], v[94:97]
	v_mfma_f32_16x16x32_bf16 v[90:93], v[156:159], v[160:163], v[90:93]
	s_waitcnt lgkmcnt(1)
	v_mfma_f32_16x16x32_bf16 v[86:89], v[168:171], v[160:163], v[86:89]
	s_add_u32 m0, s17, 0xe000
	v_lshl_add_u64 v[204:205], v[200:201], 0, s[4:5]
	global_load_lds_dwordx4 v[204:205], off
	s_waitcnt lgkmcnt(0)
	v_mfma_f32_16x16x32_bf16 v[82:85], v[172:175], v[160:163], v[82:85]
	v_mfma_f32_16x16x32_bf16 v[54:57], v[152:155], v[164:167], v[54:57]
	v_mfma_f32_16x16x32_bf16 v[42:45], v[156:159], v[164:167], v[42:45]
	s_add_u32 m0, s17, 0xf000
	v_lshl_add_u64 v[206:207], v[202:203], 0, s[4:5]
	global_load_lds_dwordx4 v[206:207], off
	v_mfma_f32_16x16x32_bf16 v[38:41], v[168:171], v[164:167], v[38:41]
	v_mfma_f32_16x16x32_bf16 v[34:37], v[172:175], v[164:167], v[34:37]
	ds_read_b128 v[160:163], v114 offset:4096
	ds_read_b128 v[164:167], v115
	s_waitcnt lgkmcnt(1)
	v_mfma_f32_16x16x32_bf16 v[78:81], v[152:155], v[160:163], v[78:81]
	v_mfma_f32_16x16x32_bf16 v[74:77], v[156:159], v[160:163], v[74:77]
	v_mfma_f32_16x16x32_bf16 v[70:73], v[168:171], v[160:163], v[70:73]
	v_mfma_f32_16x16x32_bf16 v[66:69], v[172:175], v[160:163], v[66:69]
	s_waitcnt lgkmcnt(0)
	v_mfma_f32_16x16x32_bf16 v[62:65], v[152:155], v[164:167], v[62:65]
	v_mfma_f32_16x16x32_bf16 v[58:61], v[156:159], v[164:167], v[58:61]
	v_mfma_f32_16x16x32_bf16 v[50:53], v[168:171], v[164:167], v[50:53]
	v_mfma_f32_16x16x32_bf16 v[46:49], v[172:175], v[164:167], v[46:49]
	s_setprio 0
	s_waitcnt vmcnt(0)
	s_barrier
	s_add_i32 s4, s16, 0x80
	s_min_u32 s4, s4, 0x3c0
	s_lshl_b32 s4, s4, 1
	s_setprio 1
	ds_read_b128 v[152:155], v112 offset:49152
	ds_read_b128 v[156:159], v112 offset:51200
	ds_read_b128 v[160:163], v110 offset:32768
	ds_read_b128 v[164:167], v110 offset:34816
	ds_read_b128 v[168:171], v112 offset:53248
	ds_read_b128 v[172:175], v113 offset:49152
	s_waitcnt lgkmcnt(3)
	v_mfma_f32_16x16x32_bf16 v[94:97], v[152:155], v[160:163], v[94:97]
	s_add_u32 m0, s17, 0x0
	v_lshl_add_u64 v[204:205], v[188:189], 0, s[4:5]
	global_load_lds_dwordx4 v[204:205], off
	v_mfma_f32_16x16x32_bf16 v[90:93], v[156:159], v[160:163], v[90:93]
	s_waitcnt lgkmcnt(1)
	v_mfma_f32_16x16x32_bf16 v[86:89], v[168:171], v[160:163], v[86:89]
	s_waitcnt lgkmcnt(0)
	v_mfma_f32_16x16x32_bf16 v[82:85], v[172:175], v[160:163], v[82:85]
	s_add_u32 m0, s17, 0x1000
	v_lshl_add_u64 v[206:207], v[190:191], 0, s[4:5]
	global_load_lds_dwordx4 v[206:207], off
	v_mfma_f32_16x16x32_bf16 v[54:57], v[152:155], v[164:167], v[54:57]
	v_mfma_f32_16x16x32_bf16 v[42:45], v[156:159], v[164:167], v[42:45]
	v_mfma_f32_16x16x32_bf16 v[38:41], v[168:171], v[164:167], v[38:41]
	s_add_u32 m0, s17, 0x2000
	v_lshl_add_u64 v[204:205], v[192:193], 0, s[4:5]
	global_load_lds_dwordx4 v[204:205], off
	v_mfma_f32_16x16x32_bf16 v[34:37], v[172:175], v[164:167], v[34:37]
	ds_read_b128 v[160:163], v110 offset:36864
	ds_read_b128 v[164:167], v111 offset:32768
	s_waitcnt lgkmcnt(1)
	v_mfma_f32_16x16x32_bf16 v[78:81], v[152:155], v[160:163], v[78:81]
	v_mfma_f32_16x16x32_bf16 v[74:77], v[156:159], v[160:163], v[74:77]
	s_add_u32 m0, s17, 0x3000
	v_lshl_add_u64 v[206:207], v[194:195], 0, s[4:5]
	global_load_lds_dwordx4 v[206:207], off
	v_mfma_f32_16x16x32_bf16 v[70:73], v[168:171], v[160:163], v[70:73]
	v_mfma_f32_16x16x32_bf16 v[66:69], v[172:175], v[160:163], v[66:69]
	s_waitcnt lgkmcnt(0)
	v_mfma_f32_16x16x32_bf16 v[62:65], v[152:155], v[164:167], v[62:65]
	s_add_u32 m0, s17, 0x4000
	v_lshl_add_u64 v[204:205], v[196:197], 0, s[4:5]
	global_load_lds_dwordx4 v[204:205], off
	ds_read_b128 v[152:155], v116 offset:49152
	v_mfma_f32_16x16x32_bf16 v[58:61], v[156:159], v[164:167], v[58:61]
	v_mfma_f32_16x16x32_bf16 v[50:53], v[168:171], v[164:167], v[50:53]
	v_mfma_f32_16x16x32_bf16 v[46:49], v[172:175], v[164:167], v[46:49]
	s_add_u32 m0, s17, 0x5000
	v_lshl_add_u64 v[206:207], v[198:199], 0, s[4:5]
	global_load_lds_dwordx4 v[206:207], off
	ds_read_b128 v[156:159], v116 offset:51200
	ds_read_b128 v[160:163], v114 offset:32768
	ds_read_b128 v[164:167], v114 offset:34816
	ds_read_b128 v[168:171], v116 offset:53248
	ds_read_b128 v[172:175], v117 offset:49152
	s_waitcnt lgkmcnt(3)
	v_mfma_f32_16x16x32_bf16 v[94:97], v[152:155], v[160:163], v[94:97]
	v_mfma_f32_16x16x32_bf16 v[90:93], v[156:159], v[160:163], v[90:93]
	s_waitcnt lgkmcnt(1)
	v_mfma_f32_16x16x32_bf16 v[86:89], v[168:171], v[160:163], v[86:89]
	s_add_u32 m0, s17, 0x6000
	v_lshl_add_u64 v[204:205], v[200:201], 0, s[4:5]
	global_load_lds_dwordx4 v[204:205], off
	s_waitcnt lgkmcnt(0)
	v_mfma_f32_16x16x32_bf16 v[82:85], v[172:175], v[160:163], v[82:85]
	v_mfma_f32_16x16x32_bf16 v[54:57], v[152:155], v[164:167], v[54:57]
	v_mfma_f32_16x16x32_bf16 v[42:45], v[156:159], v[164:167], v[42:45]
	s_add_u32 m0, s17, 0x7000
	v_lshl_add_u64 v[206:207], v[202:203], 0, s[4:5]
	global_load_lds_dwordx4 v[206:207], off
	v_mfma_f32_16x16x32_bf16 v[38:41], v[168:171], v[164:167], v[38:41]
	v_mfma_f32_16x16x32_bf16 v[34:37], v[172:175], v[164:167], v[34:37]
	ds_read_b128 v[160:163], v114 offset:36864
	ds_read_b128 v[164:167], v115 offset:32768
	s_waitcnt lgkmcnt(1)
	v_mfma_f32_16x16x32_bf16 v[78:81], v[152:155], v[160:163], v[78:81]
	v_mfma_f32_16x16x32_bf16 v[74:77], v[156:159], v[160:163], v[74:77]
	v_mfma_f32_16x16x32_bf16 v[70:73], v[168:171], v[160:163], v[70:73]
	v_mfma_f32_16x16x32_bf16 v[66:69], v[172:175], v[160:163], v[66:69]
	s_waitcnt lgkmcnt(0)
	v_mfma_f32_16x16x32_bf16 v[62:65], v[152:155], v[164:167], v[62:65]
	v_mfma_f32_16x16x32_bf16 v[58:61], v[156:159], v[164:167], v[58:61]
	v_mfma_f32_16x16x32_bf16 v[50:53], v[168:171], v[164:167], v[50:53]
	v_mfma_f32_16x16x32_bf16 v[46:49], v[172:175], v[164:167], v[46:49]
	s_setprio 0
	s_add_i32 s16, s16, 0x80
	s_add_i32 s15, s15, 2
	s_waitcnt vmcnt(0)
	s_barrier
	s_cmp_lt_u32 s15, 14
	s_cbranch_scc1 .Lglds_22142
	s_waitcnt vmcnt(7)
	v_or_b32_e32 v2, s14, v119
	s_waitcnt vmcnt(5)
	v_add_u32_e32 v10, s13, v118
	v_mov_b64_e32 v[4:5], s[64:65]
	v_ashrrev_i32_e32 v3, 31, v2
	v_mad_i64_i32 v[6:7], s[14:15], v10, s12, v[4:5]
	v_lshlrev_b64 v[2:3], 1, v[2:3]
	v_lshl_add_u64 v[6:7], v[6:7], 0, v[2:3]
	v_cvt_pk_bf16_f32 v8, v94, v95
	v_cvt_pk_bf16_f32 v9, v96, v97
	global_store_dwordx2 v[6:7], v[8:9], off
	v_cvt_pk_bf16_f32 v8, v90, v91
	v_cvt_pk_bf16_f32 v9, v92, v93
	global_store_dwordx2 v[6:7], v[8:9], off offset:32
	v_cvt_pk_bf16_f32 v8, v86, v87
	v_cvt_pk_bf16_f32 v9, v88, v89
	global_store_dwordx2 v[6:7], v[8:9], off offset:64
	v_cvt_pk_bf16_f32 v8, v82, v83
	v_cvt_pk_bf16_f32 v9, v84, v85
	global_store_dwordx2 v[6:7], v[8:9], off offset:96
	v_or_b32_e32 v6, 16, v10
	v_mad_i64_i32 v[6:7], s[14:15], v6, s12, v[4:5]
	v_lshl_add_u64 v[6:7], v[6:7], 0, v[2:3]
	v_cvt_pk_bf16_f32 v8, v54, v55
	v_cvt_pk_bf16_f32 v9, v56, v57
	global_store_dwordx2 v[6:7], v[8:9], off
	v_cvt_pk_bf16_f32 v8, v42, v43
	v_cvt_pk_bf16_f32 v9, v44, v45
	global_store_dwordx2 v[6:7], v[8:9], off offset:32
	v_cvt_pk_bf16_f32 v8, v38, v39
	v_cvt_pk_bf16_f32 v9, v40, v41
	global_store_dwordx2 v[6:7], v[8:9], off offset:64
	v_cvt_pk_bf16_f32 v8, v34, v35
	v_cvt_pk_bf16_f32 v9, v36, v37
	global_store_dwordx2 v[6:7], v[8:9], off offset:96
	v_or_b32_e32 v6, 32, v10
	v_mad_i64_i32 v[6:7], s[14:15], v6, s12, v[4:5]
	v_lshl_add_u64 v[6:7], v[6:7], 0, v[2:3]
	v_cvt_pk_bf16_f32 v8, v78, v79
	v_cvt_pk_bf16_f32 v9, v80, v81
	global_store_dwordx2 v[6:7], v[8:9], off
	v_cvt_pk_bf16_f32 v8, v74, v75
	v_cvt_pk_bf16_f32 v9, v76, v77
	global_store_dwordx2 v[6:7], v[8:9], off offset:32
	v_cvt_pk_bf16_f32 v8, v70, v71
	v_cvt_pk_bf16_f32 v9, v72, v73
	global_store_dwordx2 v[6:7], v[8:9], off offset:64
	v_cvt_pk_bf16_f32 v8, v66, v67
	v_cvt_pk_bf16_f32 v9, v68, v69
	global_store_dwordx2 v[6:7], v[8:9], off offset:96
	v_or_b32_e32 v6, 48, v10
	v_mad_i64_i32 v[4:5], s[14:15], v6, s12, v[4:5]
	v_lshl_add_u64 v[2:3], v[4:5], 0, v[2:3]
	v_cvt_pk_bf16_f32 v4, v62, v63
	v_cvt_pk_bf16_f32 v5, v64, v65
	global_store_dwordx2 v[2:3], v[4:5], off
	v_cvt_pk_bf16_f32 v4, v58, v59
	v_cvt_pk_bf16_f32 v5, v60, v61
	global_store_dwordx2 v[2:3], v[4:5], off offset:32
	v_cvt_pk_bf16_f32 v4, v50, v51
	v_cvt_pk_bf16_f32 v5, v52, v53
	s_add_i32 s3, s3, s2
	global_store_dwordx2 v[2:3], v[4:5], off offset:64
	v_cvt_pk_bf16_f32 v4, v46, v47
	v_cvt_pk_bf16_f32 v5, v48, v49
	s_cmpk_lt_u32 s3, 0x280
	global_store_dwordx2 v[2:3], v[4:5], off offset:96
	s_cbranch_scc1 .LBB0_664

.Lglds_26323:
	s_add_i32 s4, s14, 0x40
	s_lshl_b32 s4, s4, 1
	s_setprio 1
	ds_read_b128 v[152:155], v111 offset:16384
	ds_read_b128 v[156:159], v111 offset:18432
	ds_read_b128 v[160:163], v109
	ds_read_b128 v[164:167], v109 offset:2048
	ds_read_b128 v[168:171], v111 offset:20480
	ds_read_b128 v[172:175], v112 offset:16384
	s_waitcnt lgkmcnt(3)
	v_mfma_f32_16x16x32_bf16 v[92:95], v[152:155], v[160:163], v[92:95]
	s_add_u32 m0, s15, 0x8000
	v_lshl_add_u64 v[204:205], v[188:189], 0, s[4:5]
	global_load_lds_dwordx4 v[204:205], off
	v_mfma_f32_16x16x32_bf16 v[88:91], v[156:159], v[160:163], v[88:91]
	s_waitcnt lgkmcnt(1)
	v_mfma_f32_16x16x32_bf16 v[84:87], v[168:171], v[160:163], v[84:87]
	s_waitcnt lgkmcnt(0)
	v_mfma_f32_16x16x32_bf16 v[80:83], v[172:175], v[160:163], v[80:83]
	s_add_u32 m0, s15, 0x9000
	v_lshl_add_u64 v[206:207], v[190:191], 0, s[4:5]
	global_load_lds_dwordx4 v[206:207], off
	v_mfma_f32_16x16x32_bf16 v[76:79], v[152:155], v[164:167], v[76:79]
	v_mfma_f32_16x16x32_bf16 v[72:75], v[156:159], v[164:167], v[72:75]
	v_mfma_f32_16x16x32_bf16 v[60:63], v[168:171], v[164:167], v[60:63]
	s_add_u32 m0, s15, 0xa000
	v_lshl_add_u64 v[204:205], v[192:193], 0, s[4:5]
	global_load_lds_dwordx4 v[204:205], off
	v_mfma_f32_16x16x32_bf16 v[28:31], v[172:175], v[164:167], v[28:31]
	ds_read_b128 v[160:163], v109 offset:4096
	ds_read_b128 v[164:167], v110
	s_waitcnt lgkmcnt(1)
	v_mfma_f32_16x16x32_bf16 v[64:67], v[152:155], v[160:163], v[64:67]
	v_mfma_f32_16x16x32_bf16 v[36:39], v[156:159], v[160:163], v[36:39]
	s_add_u32 m0, s15, 0xb000
	v_lshl_add_u64 v[206:207], v[194:195], 0, s[4:5]
	global_load_lds_dwordx4 v[206:207], off
	v_mfma_f32_16x16x32_bf16 v[32:35], v[168:171], v[160:163], v[32:35]
	v_mfma_f32_16x16x32_bf16 v[16:19], v[172:175], v[160:163], v[16:19]
	s_waitcnt lgkmcnt(0)
	v_mfma_f32_16x16x32_bf16 v[12:15], v[152:155], v[164:167], v[12:15]
	s_add_u32 m0, s15, 0xc000
	v_lshl_add_u64 v[204:205], v[196:197], 0, s[4:5]
	global_load_lds_dwordx4 v[204:205], off
	ds_read_b128 v[152:155], v115 offset:16384
	v_mfma_f32_16x16x32_bf16 v[8:11], v[156:159], v[164:167], v[8:11]
	v_mfma_f32_16x16x32_bf16 v[4:7], v[168:171], v[164:167], v[4:7]
	v_mfma_f32_16x16x32_bf16 v[0:3], v[172:175], v[164:167], v[0:3]
	s_add_u32 m0, s15, 0xd000
	v_lshl_add_u64 v[206:207], v[198:199], 0, s[4:5]
	global_load_lds_dwordx4 v[206:207], off
	ds_read_b128 v[156:159], v115 offset:18432
	ds_read_b128 v[160:163], v113
	ds_read_b128 v[164:167], v113 offset:2048
	ds_read_b128 v[168:171], v115 offset:20480
	ds_read_b128 v[172:175], v116 offset:16384
	s_waitcnt lgkmcnt(3)
	v_mfma_f32_16x16x32_bf16 v[92:95], v[152:155], v[160:163], v[92:95]
	v_mfma_f32_16x16x32_bf16 v[88:91], v[156:159], v[160:163], v[88:91]
	s_waitcnt lgkmcnt(1)
	v_mfma_f32_16x16x32_bf16 v[84:87], v[168:171], v[160:163], v[84:87]
	s_add_u32 m0, s15, 0xe000
	v_lshl_add_u64 v[204:205], v[200:201], 0, s[4:5]
	global_load_lds_dwordx4 v[204:205], off
	s_waitcnt lgkmcnt(0)
	v_mfma_f32_16x16x32_bf16 v[80:83], v[172:175], v[160:163], v[80:83]
	v_mfma_f32_16x16x32_bf16 v[76:79], v[152:155], v[164:167], v[76:79]
	v_mfma_f32_16x16x32_bf16 v[72:75], v[156:159], v[164:167], v[72:75]
	s_add_u32 m0, s15, 0xf000
	v_lshl_add_u64 v[206:207], v[202:203], 0, s[4:5]
	global_load_lds_dwordx4 v[206:207], off
	v_mfma_f32_16x16x32_bf16 v[60:63], v[168:171], v[164:167], v[60:63]
	v_mfma_f32_16x16x32_bf16 v[28:31], v[172:175], v[164:167], v[28:31]
	ds_read_b128 v[160:163], v113 offset:4096
	ds_read_b128 v[164:167], v114
	s_waitcnt lgkmcnt(1)
	v_mfma_f32_16x16x32_bf16 v[64:67], v[152:155], v[160:163], v[64:67]
	v_mfma_f32_16x16x32_bf16 v[36:39], v[156:159], v[160:163], v[36:39]
	v_mfma_f32_16x16x32_bf16 v[32:35], v[168:171], v[160:163], v[32:35]
	v_mfma_f32_16x16x32_bf16 v[16:19], v[172:175], v[160:163], v[16:19]
	s_waitcnt lgkmcnt(0)
	v_mfma_f32_16x16x32_bf16 v[12:15], v[152:155], v[164:167], v[12:15]
	v_mfma_f32_16x16x32_bf16 v[8:11], v[156:159], v[164:167], v[8:11]
	v_mfma_f32_16x16x32_bf16 v[4:7], v[168:171], v[164:167], v[4:7]
	v_mfma_f32_16x16x32_bf16 v[0:3], v[172:175], v[164:167], v[0:3]
	s_setprio 0
	s_waitcnt vmcnt(0)
	s_barrier
	s_add_i32 s4, s14, 0x80
	s_min_u32 s4, s4, 0x3c0
	s_lshl_b32 s4, s4, 1
	s_setprio 1
	ds_read_b128 v[152:155], v111 offset:49152
	ds_read_b128 v[156:159], v111 offset:51200
	ds_read_b128 v[160:163], v109 offset:32768
	ds_read_b128 v[164:167], v109 offset:34816
	ds_read_b128 v[168:171], v111 offset:53248
	ds_read_b128 v[172:175], v112 offset:49152
	s_waitcnt lgkmcnt(3)
	v_mfma_f32_16x16x32_bf16 v[92:95], v[152:155], v[160:163], v[92:95]
	s_add_u32 m0, s15, 0x0
	v_lshl_add_u64 v[204:205], v[188:189], 0, s[4:5]
	global_load_lds_dwordx4 v[204:205], off
	v_mfma_f32_16x16x32_bf16 v[88:91], v[156:159], v[160:163], v[88:91]
	s_waitcnt lgkmcnt(1)
	v_mfma_f32_16x16x32_bf16 v[84:87], v[168:171], v[160:163], v[84:87]
	s_waitcnt lgkmcnt(0)
	v_mfma_f32_16x16x32_bf16 v[80:83], v[172:175], v[160:163], v[80:83]
	s_add_u32 m0, s15, 0x1000
	v_lshl_add_u64 v[206:207], v[190:191], 0, s[4:5]
	global_load_lds_dwordx4 v[206:207], off
	v_mfma_f32_16x16x32_bf16 v[76:79], v[152:155], v[164:167], v[76:79]
	v_mfma_f32_16x16x32_bf16 v[72:75], v[156:159], v[164:167], v[72:75]
	v_mfma_f32_16x16x32_bf16 v[60:63], v[168:171], v[164:167], v[60:63]
	s_add_u32 m0, s15, 0x2000
	v_lshl_add_u64 v[204:205], v[192:193], 0, s[4:5]
	global_load_lds_dwordx4 v[204:205], off
	v_mfma_f32_16x16x32_bf16 v[28:31], v[172:175], v[164:167], v[28:31]
	ds_read_b128 v[160:163], v109 offset:36864
	ds_read_b128 v[164:167], v110 offset:32768
	s_waitcnt lgkmcnt(1)
	v_mfma_f32_16x16x32_bf16 v[64:67], v[152:155], v[160:163], v[64:67]
	v_mfma_f32_16x16x32_bf16 v[36:39], v[156:159], v[160:163], v[36:39]
	s_add_u32 m0, s15, 0x3000
	v_lshl_add_u64 v[206:207], v[194:195], 0, s[4:5]
	global_load_lds_dwordx4 v[206:207], off
	v_mfma_f32_16x16x32_bf16 v[32:35], v[168:171], v[160:163], v[32:35]
	v_mfma_f32_16x16x32_bf16 v[16:19], v[172:175], v[160:163], v[16:19]
	s_waitcnt lgkmcnt(0)
	v_mfma_f32_16x16x32_bf16 v[12:15], v[152:155], v[164:167], v[12:15]
	s_add_u32 m0, s15, 0x4000
	v_lshl_add_u64 v[204:205], v[196:197], 0, s[4:5]
	global_load_lds_dwordx4 v[204:205], off
	ds_read_b128 v[152:155], v115 offset:49152
	v_mfma_f32_16x16x32_bf16 v[8:11], v[156:159], v[164:167], v[8:11]
	v_mfma_f32_16x16x32_bf16 v[4:7], v[168:171], v[164:167], v[4:7]
	v_mfma_f32_16x16x32_bf16 v[0:3], v[172:175], v[164:167], v[0:3]
	s_add_u32 m0, s15, 0x5000
	v_lshl_add_u64 v[206:207], v[198:199], 0, s[4:5]
	global_load_lds_dwordx4 v[206:207], off
	ds_read_b128 v[156:159], v115 offset:51200
	ds_read_b128 v[160:163], v113 offset:32768
	ds_read_b128 v[164:167], v113 offset:34816
	ds_read_b128 v[168:171], v115 offset:53248
	ds_read_b128 v[172:175], v116 offset:49152
	s_waitcnt lgkmcnt(3)
	v_mfma_f32_16x16x32_bf16 v[92:95], v[152:155], v[160:163], v[92:95]
	v_mfma_f32_16x16x32_bf16 v[88:91], v[156:159], v[160:163], v[88:91]
	s_waitcnt lgkmcnt(1)
	v_mfma_f32_16x16x32_bf16 v[84:87], v[168:171], v[160:163], v[84:87]
	s_add_u32 m0, s15, 0x6000
	v_lshl_add_u64 v[204:205], v[200:201], 0, s[4:5]
	global_load_lds_dwordx4 v[204:205], off
	s_waitcnt lgkmcnt(0)
	v_mfma_f32_16x16x32_bf16 v[80:83], v[172:175], v[160:163], v[80:83]
	v_mfma_f32_16x16x32_bf16 v[76:79], v[152:155], v[164:167], v[76:79]
	v_mfma_f32_16x16x32_bf16 v[72:75], v[156:159], v[164:167], v[72:75]
	s_add_u32 m0, s15, 0x7000
	v_lshl_add_u64 v[206:207], v[202:203], 0, s[4:5]
	global_load_lds_dwordx4 v[206:207], off
	v_mfma_f32_16x16x32_bf16 v[60:63], v[168:171], v[164:167], v[60:63]
	v_mfma_f32_16x16x32_bf16 v[28:31], v[172:175], v[164:167], v[28:31]
	ds_read_b128 v[160:163], v113 offset:36864
	ds_read_b128 v[164:167], v114 offset:32768
	s_waitcnt lgkmcnt(1)
	v_mfma_f32_16x16x32_bf16 v[64:67], v[152:155], v[160:163], v[64:67]
	v_mfma_f32_16x16x32_bf16 v[36:39], v[156:159], v[160:163], v[36:39]
	v_mfma_f32_16x16x32_bf16 v[32:35], v[168:171], v[160:163], v[32:35]
	v_mfma_f32_16x16x32_bf16 v[16:19], v[172:175], v[160:163], v[16:19]
	s_waitcnt lgkmcnt(0)
	v_mfma_f32_16x16x32_bf16 v[12:15], v[152:155], v[164:167], v[12:15]
	v_mfma_f32_16x16x32_bf16 v[8:11], v[156:159], v[164:167], v[8:11]
	v_mfma_f32_16x16x32_bf16 v[4:7], v[168:171], v[164:167], v[4:7]
	v_mfma_f32_16x16x32_bf16 v[0:3], v[172:175], v[164:167], v[0:3]
	s_setprio 0
	s_add_i32 s14, s14, 0x80
	s_add_i32 s13, s13, 2
	s_waitcnt vmcnt(0)
	s_barrier
	s_cmp_lt_u32 s13, 14
	s_cbranch_scc1 .Lglds_26323
	s_waitcnt vmcnt(0)
	v_or_b32_e32 v170, s12, v118
	v_add_lshl_u32 v96, v117, s11, 10
	v_readlane_b32 s12, v254, 24
	v_readlane_b32 s16, v254, 28
	v_readlane_b32 s17, v254, 29
	v_readlane_b32 s13, v254, 25
	v_readlane_b32 s14, v254, 26
	v_readlane_b32 s15, v254, 27
	v_readlane_b32 s18, v254, 30
	v_readlane_b32 s19, v254, 31
	v_readlane_b32 s20, v254, 32
	v_readlane_b32 s21, v254, 33
	v_readlane_b32 s22, v254, 34
	v_readlane_b32 s23, v254, 35
	v_readlane_b32 s24, v254, 36
	v_readlane_b32 s25, v254, 37
	v_readlane_b32 s26, v254, 38
	v_readlane_b32 s27, v254, 39
	v_lshlrev_b32_e32 v168, 2, v170
	v_mov_b32_e32 v169, v97
	v_lshlrev_b64 v[174:175], 2, v[96:97]
	v_lshl_add_u64 v[152:153], s[16:17], 0, v[174:175]
	v_lshl_add_u64 v[160:161], s[82:83], 0, v[174:175]
	v_lshl_add_u64 v[152:153], v[152:153], 0, v[168:169]
	v_lshl_add_u64 v[160:161], v[160:161], 0, v[168:169]
	global_load_dwordx4 v[120:123], v[152:153], off
	global_load_dwordx4 v[124:127], v[152:153], off offset:64
	global_load_dwordx4 v[128:131], v[152:153], off offset:128
	global_load_dwordx4 v[132:135], v[152:153], off offset:192
	v_or_b32_e32 v172, 0x4000, v96
	v_mov_b32_e32 v173, v97
	v_lshlrev_b64 v[174:175], 2, v[172:173]
	v_lshl_add_u64 v[154:155], s[16:17], 0, v[174:175]
	v_lshl_add_u64 v[162:163], s[82:83], 0, v[174:175]
	v_lshl_add_u64 v[154:155], v[154:155], 0, v[168:169]
	v_lshl_add_u64 v[162:163], v[162:163], 0, v[168:169]
	global_load_dwordx4 v[136:139], v[154:155], off
	global_load_dwordx4 v[140:143], v[154:155], off offset:64
	global_load_dwordx4 v[144:147], v[154:155], off offset:128
	global_load_dwordx4 v[148:151], v[154:155], off offset:192
	v_or_b32_e32 v172, 0x8000, v96
	v_mov_b32_e32 v173, v97
	v_lshlrev_b64 v[174:175], 2, v[172:173]
	v_lshl_add_u64 v[156:157], s[16:17], 0, v[174:175]
	v_lshl_add_u64 v[164:165], s[82:83], 0, v[174:175]
	v_lshl_add_u64 v[156:157], v[156:157], 0, v[168:169]
	v_lshl_add_u64 v[164:165], v[164:165], 0, v[168:169]
	global_load_dwordx4 v[20:23], v[156:157], off
	global_load_dwordx4 v[24:27], v[156:157], off offset:64
	global_load_dwordx4 v[40:43], v[156:157], off offset:128
	global_load_dwordx4 v[44:47], v[156:157], off offset:192
	v_or_b32_e32 v172, 0xc000, v96
	v_mov_b32_e32 v173, v97
	v_lshlrev_b64 v[174:175], 2, v[172:173]
	v_lshl_add_u64 v[158:159], s[16:17], 0, v[174:175]
	v_lshl_add_u64 v[166:167], s[82:83], 0, v[174:175]
	v_lshl_add_u64 v[158:159], v[158:159], 0, v[168:169]
	v_lshl_add_u64 v[166:167], v[166:167], 0, v[168:169]
	global_load_dwordx4 v[48:51], v[158:159], off
	global_load_dwordx4 v[52:55], v[158:159], off offset:64
	global_load_dwordx4 v[56:59], v[158:159], off offset:128
	global_load_dwordx4 v[68:71], v[158:159], off offset:192
	s_waitcnt vmcnt(15)
	v_pk_fma_f32 v[120:121], v[120:121], s[6:7], v[92:93] op_sel_hi:[1,0,1]
	v_pk_fma_f32 v[122:123], v[122:123], s[6:7], v[94:95] op_sel_hi:[1,0,1]
	s_waitcnt vmcnt(14)
	v_pk_fma_f32 v[124:125], v[124:125], s[6:7], v[88:89] op_sel_hi:[1,0,1]
	v_pk_fma_f32 v[126:127], v[126:127], s[6:7], v[90:91] op_sel_hi:[1,0,1]
	s_waitcnt vmcnt(13)
	v_pk_fma_f32 v[128:129], v[128:129], s[6:7], v[84:85] op_sel_hi:[1,0,1]
	v_pk_fma_f32 v[130:131], v[130:131], s[6:7], v[86:87] op_sel_hi:[1,0,1]
	s_waitcnt vmcnt(12)
	v_pk_fma_f32 v[132:133], v[132:133], s[6:7], v[80:81] op_sel_hi:[1,0,1]
	v_pk_fma_f32 v[134:135], v[134:135], s[6:7], v[82:83] op_sel_hi:[1,0,1]
	s_waitcnt vmcnt(11)
	v_pk_fma_f32 v[136:137], v[136:137], s[6:7], v[76:77] op_sel_hi:[1,0,1]
	v_pk_fma_f32 v[138:139], v[138:139], s[6:7], v[78:79] op_sel_hi:[1,0,1]
	s_waitcnt vmcnt(10)
	v_pk_fma_f32 v[140:141], v[140:141], s[6:7], v[72:73] op_sel_hi:[1,0,1]
	v_pk_fma_f32 v[142:143], v[142:143], s[6:7], v[74:75] op_sel_hi:[1,0,1]
	s_waitcnt vmcnt(9)
	v_pk_fma_f32 v[144:145], v[144:145], s[6:7], v[60:61] op_sel_hi:[1,0,1]
	v_pk_fma_f32 v[146:147], v[146:147], s[6:7], v[62:63] op_sel_hi:[1,0,1]
	s_waitcnt vmcnt(8)
	v_pk_fma_f32 v[148:149], v[148:149], s[6:7], v[28:29] op_sel_hi:[1,0,1]
	v_pk_fma_f32 v[150:151], v[150:151], s[6:7], v[30:31] op_sel_hi:[1,0,1]
	s_waitcnt vmcnt(7)
	v_pk_fma_f32 v[20:21], v[20:21], s[6:7], v[64:65] op_sel_hi:[1,0,1]
	v_pk_fma_f32 v[22:23], v[22:23], s[6:7], v[66:67] op_sel_hi:[1,0,1]
	s_waitcnt vmcnt(6)
	v_pk_fma_f32 v[24:25], v[24:25], s[6:7], v[36:37] op_sel_hi:[1,0,1]
	v_pk_fma_f32 v[26:27], v[26:27], s[6:7], v[38:39] op_sel_hi:[1,0,1]
	s_waitcnt vmcnt(5)
	v_pk_fma_f32 v[40:41], v[40:41], s[6:7], v[32:33] op_sel_hi:[1,0,1]
	v_pk_fma_f32 v[42:43], v[42:43], s[6:7], v[34:35] op_sel_hi:[1,0,1]
	s_waitcnt vmcnt(4)
	v_pk_fma_f32 v[44:45], v[44:45], s[6:7], v[16:17] op_sel_hi:[1,0,1]
	v_pk_fma_f32 v[46:47], v[46:47], s[6:7], v[18:19] op_sel_hi:[1,0,1]
	s_waitcnt vmcnt(3)
	v_pk_fma_f32 v[48:49], v[48:49], s[6:7], v[12:13] op_sel_hi:[1,0,1]
	v_pk_fma_f32 v[50:51], v[50:51], s[6:7], v[14:15] op_sel_hi:[1,0,1]
	s_waitcnt vmcnt(2)
	v_pk_fma_f32 v[52:53], v[52:53], s[6:7], v[8:9] op_sel_hi:[1,0,1]
	v_pk_fma_f32 v[54:55], v[54:55], s[6:7], v[10:11] op_sel_hi:[1,0,1]
	s_waitcnt vmcnt(1)
	v_pk_fma_f32 v[56:57], v[56:57], s[6:7], v[4:5] op_sel_hi:[1,0,1]
	v_pk_fma_f32 v[58:59], v[58:59], s[6:7], v[6:7] op_sel_hi:[1,0,1]
	s_waitcnt vmcnt(0)
	v_pk_fma_f32 v[68:69], v[68:69], s[6:7], v[0:1] op_sel_hi:[1,0,1]
	v_pk_fma_f32 v[70:71], v[70:71], s[6:7], v[2:3] op_sel_hi:[1,0,1]
	global_store_dwordx4 v[160:161], v[120:123], off
	global_store_dwordx4 v[160:161], v[124:127], off offset:64
	global_store_dwordx4 v[160:161], v[128:131], off offset:128
	global_store_dwordx4 v[160:161], v[132:135], off offset:192
	global_store_dwordx4 v[162:163], v[136:139], off
	global_store_dwordx4 v[162:163], v[140:143], off offset:64
	global_store_dwordx4 v[162:163], v[144:147], off offset:128
	global_store_dwordx4 v[162:163], v[148:151], off offset:192
	global_store_dwordx4 v[164:165], v[20:23], off
	global_store_dwordx4 v[164:165], v[24:27], off offset:64
	global_store_dwordx4 v[164:165], v[40:43], off offset:128
	global_store_dwordx4 v[164:165], v[44:47], off offset:192
	global_store_dwordx4 v[166:167], v[48:51], off
	global_store_dwordx4 v[166:167], v[52:55], off offset:64
	global_store_dwordx4 v[166:167], v[56:59], off offset:128
	global_store_dwordx4 v[166:167], v[68:71], off offset:192
	s_add_i32 s7, s7, s3
	s_cmpk_lt_u32 s7, 0x100
	s_cbranch_scc1 .LBB0_798

.Lglds_28042:
	s_add_i32 s6, s15, 0x40
	s_lshl_b32 s6, s6, 1
	s_setprio 1
	ds_read_b128 v[152:155], v111 offset:16384
	ds_read_b128 v[156:159], v111 offset:18432
	ds_read_b128 v[160:163], v109
	ds_read_b128 v[164:167], v109 offset:2048
	ds_read_b128 v[168:171], v111 offset:20480
	ds_read_b128 v[172:175], v112 offset:16384
	s_waitcnt lgkmcnt(3)
	v_mfma_i32_16x16x64_i8 v[92:95], v[152:155], v[160:163], v[92:95]
	s_add_u32 m0, s16, 0x8000
	v_lshl_add_u64 v[204:205], v[188:189], 0, s[6:7]
	global_load_lds_dwordx4 v[204:205], off
	v_mfma_i32_16x16x64_i8 v[88:91], v[156:159], v[160:163], v[88:91]
	s_waitcnt lgkmcnt(1)
	v_mfma_i32_16x16x64_i8 v[84:87], v[168:171], v[160:163], v[84:87]
	s_waitcnt lgkmcnt(0)
	v_mfma_i32_16x16x64_i8 v[80:83], v[172:175], v[160:163], v[80:83]
	s_add_u32 m0, s16, 0x9000
	v_lshl_add_u64 v[206:207], v[190:191], 0, s[6:7]
	global_load_lds_dwordx4 v[206:207], off
	v_mfma_i32_16x16x64_i8 v[60:63], v[152:155], v[164:167], v[60:63]
	v_mfma_i32_16x16x64_i8 v[40:43], v[156:159], v[164:167], v[40:43]
	v_mfma_i32_16x16x64_i8 v[36:39], v[168:171], v[164:167], v[36:39]
	s_add_u32 m0, s16, 0xa000
	v_lshl_add_u64 v[204:205], v[192:193], 0, s[6:7]
	global_load_lds_dwordx4 v[204:205], off
	v_mfma_i32_16x16x64_i8 v[28:31], v[172:175], v[164:167], v[28:31]
	ds_read_b128 v[160:163], v109 offset:4096
	ds_read_b128 v[164:167], v110
	s_waitcnt lgkmcnt(1)
	v_mfma_i32_16x16x64_i8 v[32:35], v[152:155], v[160:163], v[32:35]
	v_mfma_i32_16x16x64_i8 v[24:27], v[156:159], v[160:163], v[24:27]
	s_add_u32 m0, s16, 0xb000
	v_lshl_add_u64 v[206:207], v[194:195], 0, s[6:7]
	global_load_lds_dwordx4 v[206:207], off
	v_mfma_i32_16x16x64_i8 v[20:23], v[168:171], v[160:163], v[20:23]
	v_mfma_i32_16x16x64_i8 v[16:19], v[172:175], v[160:163], v[16:19]
	s_waitcnt lgkmcnt(0)
	v_mfma_i32_16x16x64_i8 v[12:15], v[152:155], v[164:167], v[12:15]
	s_add_u32 m0, s16, 0xc000
	v_lshl_add_u64 v[204:205], v[196:197], 0, s[6:7]
	global_load_lds_dwordx4 v[204:205], off
	ds_read_b128 v[152:155], v115 offset:16384
	v_mfma_i32_16x16x64_i8 v[8:11], v[156:159], v[164:167], v[8:11]
	v_mfma_i32_16x16x64_i8 v[4:7], v[168:171], v[164:167], v[4:7]
	v_mfma_i32_16x16x64_i8 v[0:3], v[172:175], v[164:167], v[0:3]
	s_add_u32 m0, s16, 0xd000
	v_lshl_add_u64 v[206:207], v[198:199], 0, s[6:7]
	global_load_lds_dwordx4 v[206:207], off
	ds_read_b128 v[156:159], v115 offset:18432
	ds_read_b128 v[160:163], v113
	ds_read_b128 v[164:167], v113 offset:2048
	ds_read_b128 v[168:171], v115 offset:20480
	ds_read_b128 v[172:175], v116 offset:16384
	s_waitcnt lgkmcnt(3)
	v_mfma_i32_16x16x64_i8 v[92:95], v[152:155], v[160:163], v[92:95]
	v_mfma_i32_16x16x64_i8 v[88:91], v[156:159], v[160:163], v[88:91]
	s_waitcnt lgkmcnt(1)
	v_mfma_i32_16x16x64_i8 v[84:87], v[168:171], v[160:163], v[84:87]
	s_add_u32 m0, s16, 0xe000
	v_lshl_add_u64 v[204:205], v[200:201], 0, s[6:7]
	global_load_lds_dwordx4 v[204:205], off
	s_waitcnt lgkmcnt(0)
	v_mfma_i32_16x16x64_i8 v[80:83], v[172:175], v[160:163], v[80:83]
	v_mfma_i32_16x16x64_i8 v[60:63], v[152:155], v[164:167], v[60:63]
	v_mfma_i32_16x16x64_i8 v[40:43], v[156:159], v[164:167], v[40:43]
	s_add_u32 m0, s16, 0xf000
	v_lshl_add_u64 v[206:207], v[202:203], 0, s[6:7]
	global_load_lds_dwordx4 v[206:207], off
	v_mfma_i32_16x16x64_i8 v[36:39], v[168:171], v[164:167], v[36:39]
	v_mfma_i32_16x16x64_i8 v[28:31], v[172:175], v[164:167], v[28:31]
	ds_read_b128 v[160:163], v113 offset:4096
	ds_read_b128 v[164:167], v114
	s_waitcnt lgkmcnt(1)
	v_mfma_i32_16x16x64_i8 v[32:35], v[152:155], v[160:163], v[32:35]
	v_mfma_i32_16x16x64_i8 v[24:27], v[156:159], v[160:163], v[24:27]
	v_mfma_i32_16x16x64_i8 v[20:23], v[168:171], v[160:163], v[20:23]
	v_mfma_i32_16x16x64_i8 v[16:19], v[172:175], v[160:163], v[16:19]
	s_waitcnt lgkmcnt(0)
	v_mfma_i32_16x16x64_i8 v[12:15], v[152:155], v[164:167], v[12:15]
	v_mfma_i32_16x16x64_i8 v[8:11], v[156:159], v[164:167], v[8:11]
	v_mfma_i32_16x16x64_i8 v[4:7], v[168:171], v[164:167], v[4:7]
	v_mfma_i32_16x16x64_i8 v[0:3], v[172:175], v[164:167], v[0:3]
	s_setprio 0
	s_waitcnt vmcnt(0)
	s_barrier
	s_add_i32 s6, s15, 0x80
	s_min_u32 s6, s6, 0x1c0
	s_lshl_b32 s6, s6, 1
	s_setprio 1
	ds_read_b128 v[152:155], v111 offset:49152
	ds_read_b128 v[156:159], v111 offset:51200
	ds_read_b128 v[160:163], v109 offset:32768
	ds_read_b128 v[164:167], v109 offset:34816
	ds_read_b128 v[168:171], v111 offset:53248
	ds_read_b128 v[172:175], v112 offset:49152
	s_waitcnt lgkmcnt(3)
	v_mfma_i32_16x16x64_i8 v[92:95], v[152:155], v[160:163], v[92:95]
	s_add_u32 m0, s16, 0x0
	v_lshl_add_u64 v[204:205], v[188:189], 0, s[6:7]
	global_load_lds_dwordx4 v[204:205], off
	v_mfma_i32_16x16x64_i8 v[88:91], v[156:159], v[160:163], v[88:91]
	s_waitcnt lgkmcnt(1)
	v_mfma_i32_16x16x64_i8 v[84:87], v[168:171], v[160:163], v[84:87]
	s_waitcnt lgkmcnt(0)
	v_mfma_i32_16x16x64_i8 v[80:83], v[172:175], v[160:163], v[80:83]
	s_add_u32 m0, s16, 0x1000
	v_lshl_add_u64 v[206:207], v[190:191], 0, s[6:7]
	global_load_lds_dwordx4 v[206:207], off
	v_mfma_i32_16x16x64_i8 v[60:63], v[152:155], v[164:167], v[60:63]
	v_mfma_i32_16x16x64_i8 v[40:43], v[156:159], v[164:167], v[40:43]
	v_mfma_i32_16x16x64_i8 v[36:39], v[168:171], v[164:167], v[36:39]
	s_add_u32 m0, s16, 0x2000
	v_lshl_add_u64 v[204:205], v[192:193], 0, s[6:7]
	global_load_lds_dwordx4 v[204:205], off
	v_mfma_i32_16x16x64_i8 v[28:31], v[172:175], v[164:167], v[28:31]
	ds_read_b128 v[160:163], v109 offset:36864
	ds_read_b128 v[164:167], v110 offset:32768
	s_waitcnt lgkmcnt(1)
	v_mfma_i32_16x16x64_i8 v[32:35], v[152:155], v[160:163], v[32:35]
	v_mfma_i32_16x16x64_i8 v[24:27], v[156:159], v[160:163], v[24:27]
	s_add_u32 m0, s16, 0x3000
	v_lshl_add_u64 v[206:207], v[194:195], 0, s[6:7]
	global_load_lds_dwordx4 v[206:207], off
	v_mfma_i32_16x16x64_i8 v[20:23], v[168:171], v[160:163], v[20:23]
	v_mfma_i32_16x16x64_i8 v[16:19], v[172:175], v[160:163], v[16:19]
	s_waitcnt lgkmcnt(0)
	v_mfma_i32_16x16x64_i8 v[12:15], v[152:155], v[164:167], v[12:15]
	s_add_u32 m0, s16, 0x4000
	v_lshl_add_u64 v[204:205], v[196:197], 0, s[6:7]
	global_load_lds_dwordx4 v[204:205], off
	ds_read_b128 v[152:155], v115 offset:49152
	v_mfma_i32_16x16x64_i8 v[8:11], v[156:159], v[164:167], v[8:11]
	v_mfma_i32_16x16x64_i8 v[4:7], v[168:171], v[164:167], v[4:7]
	v_mfma_i32_16x16x64_i8 v[0:3], v[172:175], v[164:167], v[0:3]
	s_add_u32 m0, s16, 0x5000
	v_lshl_add_u64 v[206:207], v[198:199], 0, s[6:7]
	global_load_lds_dwordx4 v[206:207], off
	ds_read_b128 v[156:159], v115 offset:51200
	ds_read_b128 v[160:163], v113 offset:32768
	ds_read_b128 v[164:167], v113 offset:34816
	ds_read_b128 v[168:171], v115 offset:53248
	ds_read_b128 v[172:175], v116 offset:49152
	s_waitcnt lgkmcnt(3)
	v_mfma_i32_16x16x64_i8 v[92:95], v[152:155], v[160:163], v[92:95]
	v_mfma_i32_16x16x64_i8 v[88:91], v[156:159], v[160:163], v[88:91]
	s_waitcnt lgkmcnt(1)
	v_mfma_i32_16x16x64_i8 v[84:87], v[168:171], v[160:163], v[84:87]
	s_add_u32 m0, s16, 0x6000
	v_lshl_add_u64 v[204:205], v[200:201], 0, s[6:7]
	global_load_lds_dwordx4 v[204:205], off
	s_waitcnt lgkmcnt(0)
	v_mfma_i32_16x16x64_i8 v[80:83], v[172:175], v[160:163], v[80:83]
	v_mfma_i32_16x16x64_i8 v[60:63], v[152:155], v[164:167], v[60:63]
	v_mfma_i32_16x16x64_i8 v[40:43], v[156:159], v[164:167], v[40:43]
	s_add_u32 m0, s16, 0x7000
	v_lshl_add_u64 v[206:207], v[202:203], 0, s[6:7]
	global_load_lds_dwordx4 v[206:207], off
	v_mfma_i32_16x16x64_i8 v[36:39], v[168:171], v[164:167], v[36:39]
	v_mfma_i32_16x16x64_i8 v[28:31], v[172:175], v[164:167], v[28:31]
	ds_read_b128 v[160:163], v113 offset:36864
	ds_read_b128 v[164:167], v114 offset:32768
	s_waitcnt lgkmcnt(1)
	v_mfma_i32_16x16x64_i8 v[32:35], v[152:155], v[160:163], v[32:35]
	v_mfma_i32_16x16x64_i8 v[24:27], v[156:159], v[160:163], v[24:27]
	v_mfma_i32_16x16x64_i8 v[20:23], v[168:171], v[160:163], v[20:23]
	v_mfma_i32_16x16x64_i8 v[16:19], v[172:175], v[160:163], v[16:19]
	s_waitcnt lgkmcnt(0)
	v_mfma_i32_16x16x64_i8 v[12:15], v[152:155], v[164:167], v[12:15]
	v_mfma_i32_16x16x64_i8 v[8:11], v[156:159], v[164:167], v[8:11]
	v_mfma_i32_16x16x64_i8 v[4:7], v[168:171], v[164:167], v[4:7]
	v_mfma_i32_16x16x64_i8 v[0:3], v[172:175], v[164:167], v[0:3]
	s_setprio 0
	s_add_i32 s15, s15, 0x80
	s_add_i32 s14, s14, 2
	s_waitcnt vmcnt(0)
	s_barrier
	s_cmp_lt_u32 s14, 6
	s_cbranch_scc1 .Lglds_28042
	v_cvt_f32_i32_e32 v92, v92
	v_cvt_f32_i32_e32 v93, v93
	v_cvt_f32_i32_e32 v94, v94
	v_cvt_f32_i32_e32 v95, v95
	v_cvt_f32_i32_e32 v88, v88
	v_cvt_f32_i32_e32 v89, v89
	v_cvt_f32_i32_e32 v90, v90
	v_cvt_f32_i32_e32 v91, v91
	v_cvt_f32_i32_e32 v84, v84
	v_cvt_f32_i32_e32 v85, v85
	v_cvt_f32_i32_e32 v86, v86
	v_cvt_f32_i32_e32 v87, v87
	v_cvt_f32_i32_e32 v80, v80
	v_cvt_f32_i32_e32 v81, v81
	v_cvt_f32_i32_e32 v82, v82
	v_cvt_f32_i32_e32 v83, v83
	v_cvt_f32_i32_e32 v60, v60
	v_cvt_f32_i32_e32 v61, v61
	v_cvt_f32_i32_e32 v62, v62
	v_cvt_f32_i32_e32 v63, v63
	v_cvt_f32_i32_e32 v40, v40
	v_cvt_f32_i32_e32 v41, v41
	v_cvt_f32_i32_e32 v42, v42
	v_cvt_f32_i32_e32 v43, v43
	v_cvt_f32_i32_e32 v36, v36
	v_cvt_f32_i32_e32 v37, v37
	v_cvt_f32_i32_e32 v38, v38
	v_cvt_f32_i32_e32 v39, v39
	v_cvt_f32_i32_e32 v28, v28
	v_cvt_f32_i32_e32 v29, v29
	v_cvt_f32_i32_e32 v30, v30
	v_cvt_f32_i32_e32 v31, v31
	v_cvt_f32_i32_e32 v32, v32
	v_cvt_f32_i32_e32 v33, v33
	v_cvt_f32_i32_e32 v34, v34
	v_cvt_f32_i32_e32 v35, v35
	v_cvt_f32_i32_e32 v24, v24
	v_cvt_f32_i32_e32 v25, v25
	v_cvt_f32_i32_e32 v26, v26
	v_cvt_f32_i32_e32 v27, v27
	v_cvt_f32_i32_e32 v20, v20
	v_cvt_f32_i32_e32 v21, v21
	v_cvt_f32_i32_e32 v22, v22
	v_cvt_f32_i32_e32 v23, v23
	v_cvt_f32_i32_e32 v16, v16
	v_cvt_f32_i32_e32 v17, v17
	v_cvt_f32_i32_e32 v18, v18
	v_cvt_f32_i32_e32 v19, v19
	v_cvt_f32_i32_e32 v12, v12
	v_cvt_f32_i32_e32 v13, v13
	v_cvt_f32_i32_e32 v14, v14
	v_cvt_f32_i32_e32 v15, v15
	v_cvt_f32_i32_e32 v8, v8
	v_cvt_f32_i32_e32 v9, v9
	v_cvt_f32_i32_e32 v10, v10
	v_cvt_f32_i32_e32 v11, v11
	v_cvt_f32_i32_e32 v4, v4
	v_cvt_f32_i32_e32 v5, v5
	v_cvt_f32_i32_e32 v6, v6
	v_cvt_f32_i32_e32 v7, v7
	v_cvt_f32_i32_e32 v0, v0
	v_cvt_f32_i32_e32 v1, v1
	v_cvt_f32_i32_e32 v2, v2
	v_cvt_f32_i32_e32 v3, v3
	s_waitcnt vmcnt(0)
	v_add_u32_e32 v96, s12, v117
	v_or_b32_e32 v146, s13, v118
	v_lshl_add_u64 v[144:145], v[96:97], 2, s[68:69]
	v_lshlrev_b32_e32 v148, 2, v146
	global_load_dword v136, v[144:145], off
	global_load_dword v138, v[144:145], off offset:64
	global_load_dword v140, v[144:145], off offset:128
	global_load_dword v142, v[144:145], off offset:192
	global_load_dwordx4 v[120:123], v148, s[0:1]
	global_load_dwordx4 v[124:127], v148, s[0:1] offset:64
	global_load_dwordx4 v[128:131], v148, s[0:1] offset:128
	global_load_dwordx4 v[132:135], v148, s[0:1] offset:192
	v_lshlrev_b32_e32 v146, 1, v146
	v_mov_b32_e32 v147, v97
	v_lshlrev_b64 v[44:45], 12, v[96:97]
	v_lshl_add_u64 v[44:45], s[64:65], 0, v[44:45]
	v_lshl_add_u64 v[44:45], v[44:45], 0, v[146:147]
	v_or_b32_e32 v52, 16, v96
	v_mov_b32_e32 v53, v97
	v_lshlrev_b64 v[46:47], 12, v[52:53]
	v_lshl_add_u64 v[46:47], s[64:65], 0, v[46:47]
	v_lshl_add_u64 v[46:47], v[46:47], 0, v[146:147]
	v_or_b32_e32 v52, 32, v96
	v_mov_b32_e32 v53, v97
	v_lshlrev_b64 v[48:49], 12, v[52:53]
	v_lshl_add_u64 v[48:49], s[64:65], 0, v[48:49]
	v_lshl_add_u64 v[48:49], v[48:49], 0, v[146:147]
	v_or_b32_e32 v52, 48, v96
	v_mov_b32_e32 v53, v97
	v_lshlrev_b64 v[50:51], 12, v[52:53]
	v_lshl_add_u64 v[50:51], s[64:65], 0, v[50:51]
	v_lshl_add_u64 v[50:51], v[50:51], 0, v[146:147]
	s_waitcnt vmcnt(0)
	v_pk_mul_f32 v[92:93], v[136:137], v[92:93] op_sel_hi:[0,1]
	v_pk_mul_f32 v[94:95], v[136:137], v[94:95] op_sel_hi:[0,1]
	v_pk_mul_f32 v[92:93], v[120:121], v[92:93]
	v_pk_mul_f32 v[94:95], v[94:95], v[122:123]
	v_cvt_pk_bf16_f32 v92, v92, v93
	v_cvt_pk_bf16_f32 v93, v94, v95
	global_store_dwordx2 v[44:45], v[92:93], off
	v_pk_mul_f32 v[88:89], v[136:137], v[88:89] op_sel_hi:[0,1]
	v_pk_mul_f32 v[90:91], v[136:137], v[90:91] op_sel_hi:[0,1]
	v_pk_mul_f32 v[88:89], v[124:125], v[88:89]
	v_pk_mul_f32 v[90:91], v[90:91], v[126:127]
	v_cvt_pk_bf16_f32 v88, v88, v89
	v_cvt_pk_bf16_f32 v89, v90, v91
	global_store_dwordx2 v[44:45], v[88:89], off offset:32
	v_pk_mul_f32 v[84:85], v[136:137], v[84:85] op_sel_hi:[0,1]
	v_pk_mul_f32 v[86:87], v[136:137], v[86:87] op_sel_hi:[0,1]
	v_pk_mul_f32 v[84:85], v[128:129], v[84:85]
	v_pk_mul_f32 v[86:87], v[86:87], v[130:131]
	v_cvt_pk_bf16_f32 v84, v84, v85
	v_cvt_pk_bf16_f32 v85, v86, v87
	global_store_dwordx2 v[44:45], v[84:85], off offset:64
	v_pk_mul_f32 v[80:81], v[136:137], v[80:81] op_sel_hi:[0,1]
	v_pk_mul_f32 v[82:83], v[136:137], v[82:83] op_sel_hi:[0,1]
	v_pk_mul_f32 v[80:81], v[132:133], v[80:81]
	v_pk_mul_f32 v[82:83], v[82:83], v[134:135]
	v_cvt_pk_bf16_f32 v80, v80, v81
	v_cvt_pk_bf16_f32 v81, v82, v83
	global_store_dwordx2 v[44:45], v[80:81], off offset:96
	v_pk_mul_f32 v[60:61], v[138:139], v[60:61] op_sel_hi:[0,1]
	v_pk_mul_f32 v[62:63], v[138:139], v[62:63] op_sel_hi:[0,1]
	v_pk_mul_f32 v[60:61], v[120:121], v[60:61]
	v_pk_mul_f32 v[62:63], v[62:63], v[122:123]
	v_cvt_pk_bf16_f32 v60, v60, v61
	v_cvt_pk_bf16_f32 v61, v62, v63
	global_store_dwordx2 v[46:47], v[60:61], off
	v_pk_mul_f32 v[40:41], v[138:139], v[40:41] op_sel_hi:[0,1]
	v_pk_mul_f32 v[42:43], v[138:139], v[42:43] op_sel_hi:[0,1]
	v_pk_mul_f32 v[40:41], v[124:125], v[40:41]
	v_pk_mul_f32 v[42:43], v[42:43], v[126:127]
	v_cvt_pk_bf16_f32 v40, v40, v41
	v_cvt_pk_bf16_f32 v41, v42, v43
	global_store_dwordx2 v[46:47], v[40:41], off offset:32
	v_pk_mul_f32 v[36:37], v[138:139], v[36:37] op_sel_hi:[0,1]
	v_pk_mul_f32 v[38:39], v[138:139], v[38:39] op_sel_hi:[0,1]
	v_pk_mul_f32 v[36:37], v[128:129], v[36:37]
	v_pk_mul_f32 v[38:39], v[38:39], v[130:131]
	v_cvt_pk_bf16_f32 v36, v36, v37
	v_cvt_pk_bf16_f32 v37, v38, v39
	global_store_dwordx2 v[46:47], v[36:37], off offset:64
	v_pk_mul_f32 v[28:29], v[138:139], v[28:29] op_sel_hi:[0,1]
	v_pk_mul_f32 v[30:31], v[138:139], v[30:31] op_sel_hi:[0,1]
	v_pk_mul_f32 v[28:29], v[132:133], v[28:29]
	v_pk_mul_f32 v[30:31], v[30:31], v[134:135]
	v_cvt_pk_bf16_f32 v28, v28, v29
	v_cvt_pk_bf16_f32 v29, v30, v31
	global_store_dwordx2 v[46:47], v[28:29], off offset:96
	v_pk_mul_f32 v[32:33], v[140:141], v[32:33] op_sel_hi:[0,1]
	v_pk_mul_f32 v[34:35], v[140:141], v[34:35] op_sel_hi:[0,1]
	v_pk_mul_f32 v[32:33], v[120:121], v[32:33]
	v_pk_mul_f32 v[34:35], v[34:35], v[122:123]
	v_cvt_pk_bf16_f32 v32, v32, v33
	v_cvt_pk_bf16_f32 v33, v34, v35
	global_store_dwordx2 v[48:49], v[32:33], off
	v_pk_mul_f32 v[24:25], v[140:141], v[24:25] op_sel_hi:[0,1]
	v_pk_mul_f32 v[26:27], v[140:141], v[26:27] op_sel_hi:[0,1]
	v_pk_mul_f32 v[24:25], v[124:125], v[24:25]
	v_pk_mul_f32 v[26:27], v[26:27], v[126:127]
	v_cvt_pk_bf16_f32 v24, v24, v25
	v_cvt_pk_bf16_f32 v25, v26, v27
	global_store_dwordx2 v[48:49], v[24:25], off offset:32
	v_pk_mul_f32 v[20:21], v[140:141], v[20:21] op_sel_hi:[0,1]
	v_pk_mul_f32 v[22:23], v[140:141], v[22:23] op_sel_hi:[0,1]
	v_pk_mul_f32 v[20:21], v[128:129], v[20:21]
	v_pk_mul_f32 v[22:23], v[22:23], v[130:131]
	v_cvt_pk_bf16_f32 v20, v20, v21
	v_cvt_pk_bf16_f32 v21, v22, v23
	global_store_dwordx2 v[48:49], v[20:21], off offset:64
	v_pk_mul_f32 v[16:17], v[140:141], v[16:17] op_sel_hi:[0,1]
	v_pk_mul_f32 v[18:19], v[140:141], v[18:19] op_sel_hi:[0,1]
	v_pk_mul_f32 v[16:17], v[132:133], v[16:17]
	v_pk_mul_f32 v[18:19], v[18:19], v[134:135]
	v_cvt_pk_bf16_f32 v16, v16, v17
	v_cvt_pk_bf16_f32 v17, v18, v19
	global_store_dwordx2 v[48:49], v[16:17], off offset:96
	v_pk_mul_f32 v[12:13], v[142:143], v[12:13] op_sel_hi:[0,1]
	v_pk_mul_f32 v[14:15], v[142:143], v[14:15] op_sel_hi:[0,1]
	v_pk_mul_f32 v[12:13], v[120:121], v[12:13]
	v_pk_mul_f32 v[14:15], v[14:15], v[122:123]
	v_cvt_pk_bf16_f32 v12, v12, v13
	v_cvt_pk_bf16_f32 v13, v14, v15
	global_store_dwordx2 v[50:51], v[12:13], off
	v_pk_mul_f32 v[8:9], v[142:143], v[8:9] op_sel_hi:[0,1]
	v_pk_mul_f32 v[10:11], v[142:143], v[10:11] op_sel_hi:[0,1]
	v_pk_mul_f32 v[8:9], v[124:125], v[8:9]
	v_pk_mul_f32 v[10:11], v[10:11], v[126:127]
	v_cvt_pk_bf16_f32 v8, v8, v9
	v_cvt_pk_bf16_f32 v9, v10, v11
	global_store_dwordx2 v[50:51], v[8:9], off offset:32
	v_pk_mul_f32 v[4:5], v[142:143], v[4:5] op_sel_hi:[0,1]
	v_pk_mul_f32 v[6:7], v[142:143], v[6:7] op_sel_hi:[0,1]
	v_pk_mul_f32 v[4:5], v[128:129], v[4:5]
	v_pk_mul_f32 v[6:7], v[6:7], v[130:131]
	v_cvt_pk_bf16_f32 v4, v4, v5
	v_cvt_pk_bf16_f32 v5, v6, v7
	global_store_dwordx2 v[50:51], v[4:5], off offset:64
	v_pk_mul_f32 v[0:1], v[142:143], v[0:1] op_sel_hi:[0,1]
	v_pk_mul_f32 v[2:3], v[142:143], v[2:3] op_sel_hi:[0,1]
	v_pk_mul_f32 v[0:1], v[132:133], v[0:1]
	v_pk_mul_f32 v[2:3], v[2:3], v[134:135]
	v_cvt_pk_bf16_f32 v0, v0, v1
	v_cvt_pk_bf16_f32 v1, v2, v3
	global_store_dwordx2 v[50:51], v[0:1], off offset:96
	s_add_i32 s8, s8, s3
	s_cmpk_lt_u32 s8, 0x200
	s_cbranch_scc1 .LBB0_889
